# m33: m20 + bundle of individually validated neutral edits (residual-epilogue second-half loads hoisted above first-half stores, SwiGLU statistic loads before the alignment barrier, leading wave half s
# baseline (speedup 1.0000x reference)
; __device__ __forceinline__ unsigned cvtpk(float lo, float hi) { f32x2_t v = {lo, hi}; bf16x2_t b = __builtin_convertvector(v, bf16x2_t); return __builtin_bit_cast(unsigned, b); }
;     __device__ __forceinline__ void operator()(const f32x4 (&acc)[2][2][4][2], const pg8::Unit& u, int wr, int wc, int fr, int fq) const {
;         const int row0 = u.pm * 256 + wr * 64 + fr, col0 = u.pn * 256 + wc * 32 + 8 * fq;
; #pragma unroll
;         for (int ai = 0; ai < 2; ++ai) {
;             f32x4 xa[4][2][2];
; #pragma unroll
;             for (int m = 0; m < 4; ++m)
; #pragma unroll
;                 for (int bj = 0; bj < 2; ++bj) { const size_t idx = (size_t)(row0 + ai * 128 + m * 16) * DM + col0 + bj * 128;
;                     xa[m][bj][0] = *(const f32x4*)(xin + idx); xa[m][bj][1] = *(const f32x4*)(xin + idx + 4); }
; #pragma unroll
;             for (int m = 0; m < 4; ++m) {
;                 const int row = row0 + ai * 128 + m * 16;
;                 float sq = 0.f;
; #pragma unroll
;                 for (int bj = 0; bj < 2; ++bj) {
;                     const size_t idx = (size_t)row * DM + col0 + bj * 128;
;                     const f32x4 a0 = xa[m][bj][0], a1 = xa[m][bj][1];
;                     const f32x4 v0 = a0 + acc[ai][bj][m][0] * scale, v1 = a1 + acc[ai][bj][m][1] * scale;
;                     if (!last) { *(f32x4*)(xout + idx) = v0; *(f32x4*)(xout + idx + 4) = v1; }
;                     *(u32x4*)(xb + idx) = (u32x4){cvtpk(v0[0], v0[1]), cvtpk(v0[2], v0[3]), cvtpk(v1[0], v1[1]), cvtpk(v1[2], v1[3])};
;                     sq += (v0[0] * v0[0] + v0[1] * v0[1]) + (v0[2] * v0[2] + v0[3] * v0[3]) + (v1[0] * v1[0] + v1[1] * v1[1]) + (v1[2] * v1[2] + v1[3] * v1[3]);
;                 }
.LBB0_113:
	v_lshl_add_u32 v216, s53, 8, v239
	v_lshl_or_b32 v212, s18, 8, v241
	v_ashrrev_i32_e32 v213, 31, v212
	v_ashrrev_i32_e32 v217, 31, v216
	v_lshl_add_u64 v[214:215], v[212:213], 2, s[54:55]
	v_lshlrev_b64 v[130:131], 12, v[216:217]
	v_or_b32_e32 v222, 16, v216
	v_lshl_add_u64 v[130:131], v[214:215], 0, v[130:131]
	v_ashrrev_i32_e32 v223, 31, v222
	global_load_dwordx4 v[244:247], v[130:131], off offset:16
	global_load_dwordx4 v[248:251], v[130:131], off
	global_load_dwordx4 v[178:181], v[130:131], off offset:528
	global_load_dwordx4 v[182:185], v[130:131], off offset:512
	v_lshlrev_b64 v[130:131], 12, v[222:223]
	v_or_b32_e32 v220, 32, v216
	v_lshl_add_u64 v[130:131], v[214:215], 0, v[130:131]
	v_ashrrev_i32_e32 v221, 31, v220
	global_load_dwordx4 v[170:173], v[130:131], off offset:16
	global_load_dwordx4 v[174:177], v[130:131], off
	global_load_dwordx4 v[162:165], v[130:131], off offset:528
	global_load_dwordx4 v[166:169], v[130:131], off offset:512
	v_lshlrev_b64 v[130:131], 12, v[220:221]
	v_or_b32_e32 v218, 48, v216
	v_lshl_add_u64 v[130:131], v[214:215], 0, v[130:131]
	v_ashrrev_i32_e32 v219, 31, v218
	global_load_dwordx4 v[154:157], v[130:131], off offset:16
	global_load_dwordx4 v[158:161], v[130:131], off
	global_load_dwordx4 v[146:149], v[130:131], off offset:528
	global_load_dwordx4 v[150:153], v[130:131], off offset:512
	v_lshlrev_b64 v[130:131], 12, v[218:219]
	v_lshl_add_u64 v[134:135], v[214:215], 0, v[130:131]
	global_load_dwordx4 v[138:141], v[134:135], off offset:16
	global_load_dwordx4 v[142:145], v[134:135], off
	global_load_dwordx4 v[130:133], v[134:135], off offset:528
	s_nop 0
	global_load_dwordx4 v[134:137], v[134:135], off offset:512
	v_cndmask_b32_e64 v224, 0, 1, s[88:89]
	v_cmp_ne_u32_e64 s[44:45], 1, v224
	v_lshlrev_b64 v[224:225], 10, v[216:217]
	v_mov_b32_e32 v205, v204
	v_lshl_add_u64 v[224:225], v[224:225], 0, v[212:213]
	s_andn2_b64 vcc, exec, s[88:89]
	v_lshl_add_u64 v[226:227], v[224:225], 2, s[84:85]
	s_waitcnt vmcnt(0)
	v_pk_fma_f32 v[124:125], v[204:205], v[124:125], v[246:247]
	v_pk_fma_f32 v[128:129], v[204:205], v[128:129], v[250:251]
	v_pk_fma_f32 v[126:127], v[206:207], v[126:127], v[248:249]
	v_pk_fma_f32 v[122:123], v[206:207], v[122:123], v[244:245]
	v_pk_fma_f32 v[120:121], v[204:205], v[120:121], v[184:185]
	v_pk_fma_f32 v[118:119], v[206:207], v[118:119], v[182:183]
	v_pk_fma_f32 v[116:117], v[204:205], v[116:117], v[180:181]
	v_pk_fma_f32 v[114:115], v[206:207], v[114:115], v[178:179]
	v_pk_fma_f32 v[112:113], v[204:205], v[112:113], v[176:177]
	v_pk_fma_f32 v[110:111], v[206:207], v[110:111], v[174:175]
	v_pk_fma_f32 v[108:109], v[204:205], v[108:109], v[172:173]
	v_pk_fma_f32 v[106:107], v[206:207], v[106:107], v[170:171]
	v_pk_fma_f32 v[104:105], v[204:205], v[104:105], v[168:169]
	v_pk_fma_f32 v[102:103], v[206:207], v[102:103], v[166:167]
	v_pk_fma_f32 v[100:101], v[204:205], v[100:101], v[164:165]
	v_pk_fma_f32 v[98:99], v[206:207], v[98:99], v[162:163]
	v_pk_fma_f32 v[96:97], v[204:205], v[96:97], v[160:161]
	v_pk_fma_f32 v[94:95], v[206:207], v[94:95], v[158:159]
	v_pk_fma_f32 v[92:93], v[204:205], v[92:93], v[156:157]
	v_pk_fma_f32 v[90:91], v[206:207], v[90:91], v[154:155]
	v_pk_fma_f32 v[88:89], v[204:205], v[88:89], v[152:153]
	v_pk_fma_f32 v[86:87], v[206:207], v[86:87], v[150:151]
	v_pk_fma_f32 v[84:85], v[204:205], v[84:85], v[148:149]
	v_pk_fma_f32 v[82:83], v[206:207], v[82:83], v[146:147]
	v_pk_fma_f32 v[80:81], v[204:205], v[80:81], v[144:145]
	v_pk_fma_f32 v[78:79], v[206:207], v[78:79], v[142:143]
	v_pk_fma_f32 v[76:77], v[204:205], v[76:77], v[140:141]
	v_pk_fma_f32 v[74:75], v[206:207], v[74:75], v[138:139]
	v_pk_fma_f32 v[72:73], v[204:205], v[72:73], v[136:137]
	v_pk_fma_f32 v[70:71], v[206:207], v[70:71], v[134:135]
	v_pk_fma_f32 v[68:69], v[204:205], v[68:69], v[132:133]
	v_pk_fma_f32 v[66:67], v[206:207], v[66:67], v[130:131]
	v_add_u32_e32 v182, 0x80, v216
	v_ashrrev_i32_e32 v183, 31, v182
	v_lshlrev_b64 v[180:181], 12, v[182:183]
	v_lshl_add_u64 v[180:181], v[214:215], 0, v[180:181]
	global_load_dwordx4 v[132:135], v[180:181], off offset:16
	global_load_dwordx4 v[136:139], v[180:181], off
	global_load_dwordx4 v[140:143], v[180:181], off offset:528
	global_load_dwordx4 v[144:147], v[180:181], off offset:512
	v_add_u32_e32 v182, 0x90, v216
	v_ashrrev_i32_e32 v183, 31, v182
	v_lshlrev_b64 v[184:185], 12, v[182:183]
	v_lshl_add_u64 v[184:185], v[214:215], 0, v[184:185]
	global_load_dwordx4 v[148:151], v[184:185], off offset:16
	global_load_dwordx4 v[152:155], v[184:185], off
	global_load_dwordx4 v[156:159], v[184:185], off offset:528
	global_load_dwordx4 v[160:163], v[184:185], off offset:512
	v_add_u32_e32 v182, 0xa0, v216
	v_ashrrev_i32_e32 v183, 31, v182
	v_lshlrev_b64 v[180:181], 12, v[182:183]
	v_lshl_add_u64 v[180:181], v[214:215], 0, v[180:181]
	global_load_dwordx4 v[164:167], v[180:181], off offset:16
	global_load_dwordx4 v[168:171], v[180:181], off
	global_load_dwordx4 v[172:175], v[180:181], off offset:528
	global_load_dwordx4 v[176:179], v[180:181], off offset:512
	s_cbranch_vccnz .LBB0_115
	global_store_dwordx4 v[226:227], v[126:129], off
	global_store_dwordx4 v[226:227], v[122:125], off offset:16
.LBB0_115:
	v_cvt_pk_bf16_f32 v244, v126, v127
	v_cvt_pk_bf16_f32 v245, v128, v129
	v_cvt_pk_bf16_f32 v246, v122, v123
	v_cvt_pk_bf16_f32 v247, v124, v125
	v_lshl_add_u64 v[248:249], v[224:225], 1, s[74:75]
	s_and_b64 vcc, exec, s[44:45]
	global_store_dwordx4 v[248:249], v[244:247], off
	s_cbranch_vccnz .LBB0_117
	global_store_dwordx4 v[226:227], v[118:121], off offset:512
	global_store_dwordx4 v[226:227], v[114:117], off offset:528

; __device__ __forceinline__ unsigned cvtpk(float lo, float hi) { f32x2_t v = {lo, hi}; bf16x2_t b = __builtin_convertvector(v, bf16x2_t); return __builtin_bit_cast(unsigned, b); }
;     __device__ __forceinline__ void operator()(const f32x4 (&acc)[2][2][4][2], const pg8::Unit& u, int wr, int wc, int fr, int fq) const {
;     ...
;             for (int m = 0; m < 4; ++m) {
;                 const int row = row0 + ai * 128 + m * 16;
;                 float sq = 0.f;
; #pragma unroll
;                 for (int bj = 0; bj < 2; ++bj) {
;                     const size_t idx = (size_t)row * DM + col0 + bj * 128;
;                     const f32x4 a0 = xa[m][bj][0], a1 = xa[m][bj][1];
;                     const f32x4 v0 = a0 + acc[ai][bj][m][0] * scale, v1 = a1 + acc[ai][bj][m][1] * scale;
;                     if (!last) { *(f32x4*)(xout + idx) = v0; *(f32x4*)(xout + idx + 4) = v1; }
;                     *(u32x4*)(xb + idx) = (u32x4){cvtpk(v0[0], v0[1]), cvtpk(v0[2], v0[3]), cvtpk(v1[0], v1[1]), cvtpk(v1[2], v1[3])};
;                     sq += (v0[0] * v0[0] + v0[1] * v0[1]) + (v0[2] * v0[2] + v0[3] * v0[3]) + (v1[0] * v1[0] + v1[1] * v1[1]) + (v1[2] * v1[2] + v1[3] * v1[3]);
;                 }
;                 sq = xrow16_sum(sq);
;                 if (fq == 0) ss[(size_t)row * 16 + u.pn * 4 + wc] = sq;
.LBB0_119:
	s_or_b64 exec, exec, s[98:99]
	v_lshlrev_b64 v[114:115], 10, v[222:223]
	v_lshl_add_u64 v[114:115], v[114:115], 0, v[212:213]
	v_mov_b32_e32 v205, v204
	s_and_b64 vcc, exec, s[44:45]
	v_lshl_add_u64 v[116:117], v[114:115], 2, s[84:85]
	s_cbranch_vccnz .LBB0_121
	global_store_dwordx4 v[116:117], v[110:113], off
	global_store_dwordx4 v[116:117], v[106:109], off offset:16
.LBB0_121:
	v_cvt_pk_bf16_f32 v118, v110, v111
	v_cvt_pk_bf16_f32 v119, v112, v113
	v_cvt_pk_bf16_f32 v120, v106, v107
	v_cvt_pk_bf16_f32 v121, v108, v109
	v_lshl_add_u64 v[122:123], v[114:115], 1, s[74:75]
	s_and_b64 vcc, exec, s[44:45]
	global_store_dwordx4 v[122:123], v[118:121], off
	s_cbranch_vccnz .LBB0_123
	global_store_dwordx4 v[116:117], v[102:105], off offset:512
	global_store_dwordx4 v[116:117], v[98:101], off offset:528

; __device__ __forceinline__ unsigned cvtpk(float lo, float hi) { f32x2_t v = {lo, hi}; bf16x2_t b = __builtin_convertvector(v, bf16x2_t); return __builtin_bit_cast(unsigned, b); }
;     __device__ __forceinline__ void operator()(const f32x4 (&acc)[2][2][4][2], const pg8::Unit& u, int wr, int wc, int fr, int fq) const {
;     ...
;             for (int m = 0; m < 4; ++m) {
;                 const int row = row0 + ai * 128 + m * 16;
;                 float sq = 0.f;
; #pragma unroll
;                 for (int bj = 0; bj < 2; ++bj) {
;                     const size_t idx = (size_t)row * DM + col0 + bj * 128;
;                     const f32x4 a0 = xa[m][bj][0], a1 = xa[m][bj][1];
;                     const f32x4 v0 = a0 + acc[ai][bj][m][0] * scale, v1 = a1 + acc[ai][bj][m][1] * scale;
;                     if (!last) { *(f32x4*)(xout + idx) = v0; *(f32x4*)(xout + idx + 4) = v1; }
;                     *(u32x4*)(xb + idx) = (u32x4){cvtpk(v0[0], v0[1]), cvtpk(v0[2], v0[3]), cvtpk(v1[0], v1[1]), cvtpk(v1[2], v1[3])};
;                     sq += (v0[0] * v0[0] + v0[1] * v0[1]) + (v0[2] * v0[2] + v0[3] * v0[3]) + (v1[0] * v1[0] + v1[1] * v1[1]) + (v1[2] * v1[2] + v1[3] * v1[3]);
;                 }
;                 sq = xrow16_sum(sq);
;                 if (fq == 0) ss[(size_t)row * 16 + u.pn * 4 + wc] = sq;
.LBB0_125:
	s_or_b64 exec, exec, s[98:99]
	v_lshlrev_b64 v[98:99], 10, v[220:221]
	v_lshl_add_u64 v[98:99], v[98:99], 0, v[212:213]
	v_mov_b32_e32 v205, v204
	s_and_b64 vcc, exec, s[44:45]
	v_lshl_add_u64 v[100:101], v[98:99], 2, s[84:85]
	s_cbranch_vccnz .LBB0_127
	global_store_dwordx4 v[100:101], v[94:97], off
	global_store_dwordx4 v[100:101], v[90:93], off offset:16
.LBB0_127:
	v_cvt_pk_bf16_f32 v102, v94, v95
	v_cvt_pk_bf16_f32 v103, v96, v97
	v_cvt_pk_bf16_f32 v104, v90, v91
	v_cvt_pk_bf16_f32 v105, v92, v93
	v_lshl_add_u64 v[106:107], v[98:99], 1, s[74:75]
	s_and_b64 vcc, exec, s[44:45]
	global_store_dwordx4 v[106:107], v[102:105], off
	s_cbranch_vccnz .LBB0_129
	global_store_dwordx4 v[100:101], v[86:89], off offset:512
	global_store_dwordx4 v[100:101], v[82:85], off offset:528

; __device__ __forceinline__ unsigned cvtpk(float lo, float hi) { f32x2_t v = {lo, hi}; bf16x2_t b = __builtin_convertvector(v, bf16x2_t); return __builtin_bit_cast(unsigned, b); }
;     __device__ __forceinline__ void operator()(const f32x4 (&acc)[2][2][4][2], const pg8::Unit& u, int wr, int wc, int fr, int fq) const {
;     ...
;             for (int m = 0; m < 4; ++m) {
;                 const int row = row0 + ai * 128 + m * 16;
;                 float sq = 0.f;
; #pragma unroll
;                 for (int bj = 0; bj < 2; ++bj) {
;                     const size_t idx = (size_t)row * DM + col0 + bj * 128;
;                     const f32x4 a0 = xa[m][bj][0], a1 = xa[m][bj][1];
;                     const f32x4 v0 = a0 + acc[ai][bj][m][0] * scale, v1 = a1 + acc[ai][bj][m][1] * scale;
;                     if (!last) { *(f32x4*)(xout + idx) = v0; *(f32x4*)(xout + idx + 4) = v1; }
;                     *(u32x4*)(xb + idx) = (u32x4){cvtpk(v0[0], v0[1]), cvtpk(v0[2], v0[3]), cvtpk(v1[0], v1[1]), cvtpk(v1[2], v1[3])};
;                     sq += (v0[0] * v0[0] + v0[1] * v0[1]) + (v0[2] * v0[2] + v0[3] * v0[3]) + (v1[0] * v1[0] + v1[1] * v1[1]) + (v1[2] * v1[2] + v1[3] * v1[3]);
;                 }
;                 sq = xrow16_sum(sq);
;                 if (fq == 0) ss[(size_t)row * 16 + u.pn * 4 + wc] = sq;
.LBB0_131:
	s_or_b64 exec, exec, s[98:99]
	v_lshlrev_b64 v[82:83], 10, v[218:219]
	v_lshl_add_u64 v[82:83], v[82:83], 0, v[212:213]
	v_mov_b32_e32 v205, v204
	s_and_b64 vcc, exec, s[44:45]
	v_lshl_add_u64 v[84:85], v[82:83], 2, s[84:85]
	s_cbranch_vccnz .LBB0_133
	global_store_dwordx4 v[84:85], v[78:81], off
	global_store_dwordx4 v[84:85], v[74:77], off offset:16
.LBB0_133:
	v_cvt_pk_bf16_f32 v86, v78, v79
	v_cvt_pk_bf16_f32 v87, v80, v81
	v_cvt_pk_bf16_f32 v88, v74, v75
	v_cvt_pk_bf16_f32 v89, v76, v77
	v_lshl_add_u64 v[90:91], v[82:83], 1, s[74:75]
	s_and_b64 vcc, exec, s[44:45]
	global_store_dwordx4 v[90:91], v[86:89], off
	s_cbranch_vccnz .LBB0_135
	global_store_dwordx4 v[84:85], v[70:73], off offset:512
	global_store_dwordx4 v[84:85], v[66:69], off offset:528

; __device__ __forceinline__ unsigned cvtpk(float lo, float hi) { f32x2_t v = {lo, hi}; bf16x2_t b = __builtin_convertvector(v, bf16x2_t); return __builtin_bit_cast(unsigned, b); }
;     __device__ __forceinline__ void operator()(const f32x4 (&acc)[2][2][4][2], const pg8::Unit& u, int wr, int wc, int fr, int fq) const {
;     ...
;                 for (int bj = 0; bj < 2; ++bj) { const size_t idx = (size_t)(row0 + ai * 128 + m * 16) * DM + col0 + bj * 128;
;                     xa[m][bj][0] = *(const f32x4*)(xin + idx); xa[m][bj][1] = *(const f32x4*)(xin + idx + 4); }
; #pragma unroll
;             for (int m = 0; m < 4; ++m) {
;                 const int row = row0 + ai * 128 + m * 16;
;                 float sq = 0.f;
; #pragma unroll
;                 for (int bj = 0; bj < 2; ++bj) {
;                     const size_t idx = (size_t)row * DM + col0 + bj * 128;
;                     const f32x4 a0 = xa[m][bj][0], a1 = xa[m][bj][1];
;                     const f32x4 v0 = a0 + acc[ai][bj][m][0] * scale, v1 = a1 + acc[ai][bj][m][1] * scale;
;                     if (!last) { *(f32x4*)(xout + idx) = v0; *(f32x4*)(xout + idx + 4) = v1; }
;                     *(u32x4*)(xb + idx) = (u32x4){cvtpk(v0[0], v0[1]), cvtpk(v0[2], v0[3]), cvtpk(v1[0], v1[1]), cvtpk(v1[2], v1[3])};
;                     sq += (v0[0] * v0[0] + v0[1] * v0[1]) + (v0[2] * v0[2] + v0[3] * v0[3]) + (v1[0] * v1[0] + v1[1] * v1[1]) + (v1[2] * v1[2] + v1[3] * v1[3]);
;                 }
;                 sq = xrow16_sum(sq);
;                 if (fq == 0) ss[(size_t)row * 16 + u.pn * 4 + wc] = sq;
.LBB0_137:
	s_or_b64 exec, exec, s[98:99]
	v_add_u32_e32 v128, 0x80, v216
	v_ashrrev_i32_e32 v129, 31, v128
	v_add_u32_e32 v126, 0x90, v216
	v_ashrrev_i32_e32 v127, 31, v126
	v_add_u32_e32 v124, 0xa0, v216
	v_ashrrev_i32_e32 v125, 31, v124
	v_add_u32_e32 v122, 0xb0, v216
	v_ashrrev_i32_e32 v123, 31, v122
	v_lshlrev_b64 v[66:67], 12, v[122:123]
	v_lshl_add_u64 v[70:71], v[214:215], 0, v[66:67]
	global_load_dwordx4 v[74:77], v[70:71], off offset:16
	global_load_dwordx4 v[78:81], v[70:71], off
	global_load_dwordx4 v[66:69], v[70:71], off offset:528
	s_nop 0
	global_load_dwordx4 v[70:73], v[70:71], off offset:512
	v_lshlrev_b64 v[130:131], 10, v[128:129]
	v_mov_b32_e32 v205, v204
	v_lshl_add_u64 v[130:131], v[130:131], 0, v[212:213]
	s_and_b64 vcc, exec, s[44:45]
	s_cmp_lg_u64 s[88:89], 0
	s_cbranch_scc0 .Lres_w1_last
	s_waitcnt vmcnt(32)
	s_branch .Lres_w1_done
.Lres_w1_last:
	s_waitcnt vmcnt(16)
.Lres_w1_done:
	v_pk_fma_f32 v[60:61], v[204:205], v[60:61], v[134:135]
	v_pk_fma_f32 v[64:65], v[204:205], v[64:65], v[138:139]
	v_pk_fma_f32 v[62:63], v[206:207], v[62:63], v[136:137]
	v_pk_fma_f32 v[58:59], v[206:207], v[58:59], v[132:133]
	v_lshl_add_u64 v[132:133], v[130:131], 2, s[84:85]
	s_cbranch_vccnz .LBB0_139
	global_store_dwordx4 v[132:133], v[62:65], off
	global_store_dwordx4 v[132:133], v[58:61], off offset:16
.LBB0_139:
	v_cvt_pk_bf16_f32 v134, v62, v63
	v_cvt_pk_bf16_f32 v135, v64, v65
	v_cvt_pk_bf16_f32 v136, v58, v59
	v_cvt_pk_bf16_f32 v137, v60, v61
	v_lshl_add_u64 v[138:139], v[130:131], 1, s[74:75]
	v_pk_fma_f32 v[56:57], v[204:205], v[56:57], v[146:147]
	v_pk_fma_f32 v[54:55], v[206:207], v[54:55], v[144:145]
	v_pk_fma_f32 v[52:53], v[204:205], v[52:53], v[142:143]
	s_and_b64 vcc, exec, s[44:45]
	v_pk_fma_f32 v[50:51], v[206:207], v[50:51], v[140:141]
	global_store_dwordx4 v[138:139], v[134:137], off
	s_cbranch_vccnz .LBB0_141
	global_store_dwordx4 v[132:133], v[54:57], off offset:512
	global_store_dwordx4 v[132:133], v[50:53], off offset:528

; __device__ __forceinline__ unsigned cvtpk(float lo, float hi) { f32x2_t v = {lo, hi}; bf16x2_t b = __builtin_convertvector(v, bf16x2_t); return __builtin_bit_cast(unsigned, b); }
;     __device__ __forceinline__ void operator()(const f32x4 (&acc)[2][2][4][2], const pg8::Unit& u, int wr, int wc, int fr, int fq) const {
;     ...
;             for (int m = 0; m < 4; ++m) {
;                 const int row = row0 + ai * 128 + m * 16;
;                 float sq = 0.f;
; #pragma unroll
;                 for (int bj = 0; bj < 2; ++bj) {
;                     const size_t idx = (size_t)row * DM + col0 + bj * 128;
;                     const f32x4 a0 = xa[m][bj][0], a1 = xa[m][bj][1];
;                     const f32x4 v0 = a0 + acc[ai][bj][m][0] * scale, v1 = a1 + acc[ai][bj][m][1] * scale;
;                     if (!last) { *(f32x4*)(xout + idx) = v0; *(f32x4*)(xout + idx + 4) = v1; }
;                     *(u32x4*)(xb + idx) = (u32x4){cvtpk(v0[0], v0[1]), cvtpk(v0[2], v0[3]), cvtpk(v1[0], v1[1]), cvtpk(v1[2], v1[3])};
;                     sq += (v0[0] * v0[0] + v0[1] * v0[1]) + (v0[2] * v0[2] + v0[3] * v0[3]) + (v1[0] * v1[0] + v1[1] * v1[1]) + (v1[2] * v1[2] + v1[3] * v1[3]);
;                 }
;                 sq = xrow16_sum(sq);
;                 if (fq == 0) ss[(size_t)row * 16 + u.pn * 4 + wc] = sq;
.LBB0_143:
	s_or_b64 exec, exec, s[98:99]
	v_lshlrev_b64 v[50:51], 10, v[126:127]
	v_lshl_add_u64 v[50:51], v[50:51], 0, v[212:213]
	v_mov_b32_e32 v205, v204
	v_pk_fma_f32 v[48:49], v[204:205], v[48:49], v[154:155]
	v_pk_fma_f32 v[46:47], v[206:207], v[46:47], v[152:153]
	v_pk_fma_f32 v[44:45], v[204:205], v[44:45], v[150:151]
	v_pk_fma_f32 v[42:43], v[206:207], v[42:43], v[148:149]
	s_and_b64 vcc, exec, s[44:45]
	v_lshl_add_u64 v[52:53], v[50:51], 2, s[84:85]
	s_cbranch_vccnz .LBB0_145
	global_store_dwordx4 v[52:53], v[46:49], off
	global_store_dwordx4 v[52:53], v[42:45], off offset:16
.LBB0_145:
	v_cvt_pk_bf16_f32 v54, v46, v47
	v_cvt_pk_bf16_f32 v55, v48, v49
	v_cvt_pk_bf16_f32 v56, v42, v43
	v_cvt_pk_bf16_f32 v57, v44, v45
	v_lshl_add_u64 v[58:59], v[50:51], 1, s[74:75]
	v_pk_fma_f32 v[40:41], v[204:205], v[40:41], v[162:163]
	v_pk_fma_f32 v[38:39], v[206:207], v[38:39], v[160:161]
	v_pk_fma_f32 v[36:37], v[204:205], v[36:37], v[158:159]
	s_and_b64 vcc, exec, s[44:45]
	v_pk_fma_f32 v[34:35], v[206:207], v[34:35], v[156:157]
	global_store_dwordx4 v[58:59], v[54:57], off
	s_cbranch_vccnz .LBB0_147
	global_store_dwordx4 v[52:53], v[38:41], off offset:512
	global_store_dwordx4 v[52:53], v[34:37], off offset:528

; __device__ __forceinline__ unsigned cvtpk(float lo, float hi) { f32x2_t v = {lo, hi}; bf16x2_t b = __builtin_convertvector(v, bf16x2_t); return __builtin_bit_cast(unsigned, b); }
;     __device__ __forceinline__ void operator()(const f32x4 (&acc)[2][2][4][2], const pg8::Unit& u, int wr, int wc, int fr, int fq) const {
;     ...
;             for (int m = 0; m < 4; ++m) {
;                 const int row = row0 + ai * 128 + m * 16;
;                 float sq = 0.f;
; #pragma unroll
;                 for (int bj = 0; bj < 2; ++bj) {
;                     const size_t idx = (size_t)row * DM + col0 + bj * 128;
;                     const f32x4 a0 = xa[m][bj][0], a1 = xa[m][bj][1];
;                     const f32x4 v0 = a0 + acc[ai][bj][m][0] * scale, v1 = a1 + acc[ai][bj][m][1] * scale;
;                     if (!last) { *(f32x4*)(xout + idx) = v0; *(f32x4*)(xout + idx + 4) = v1; }
;                     *(u32x4*)(xb + idx) = (u32x4){cvtpk(v0[0], v0[1]), cvtpk(v0[2], v0[3]), cvtpk(v1[0], v1[1]), cvtpk(v1[2], v1[3])};
;                     sq += (v0[0] * v0[0] + v0[1] * v0[1]) + (v0[2] * v0[2] + v0[3] * v0[3]) + (v1[0] * v1[0] + v1[1] * v1[1]) + (v1[2] * v1[2] + v1[3] * v1[3]);
;                 }
;                 sq = xrow16_sum(sq);
;                 if (fq == 0) ss[(size_t)row * 16 + u.pn * 4 + wc] = sq;
.LBB0_149:
	s_or_b64 exec, exec, s[98:99]
	v_lshlrev_b64 v[34:35], 10, v[124:125]
	v_lshl_add_u64 v[34:35], v[34:35], 0, v[212:213]
	v_mov_b32_e32 v205, v204
	v_pk_fma_f32 v[32:33], v[204:205], v[32:33], v[170:171]
	v_pk_fma_f32 v[30:31], v[206:207], v[30:31], v[168:169]
	v_pk_fma_f32 v[28:29], v[204:205], v[28:29], v[166:167]
	v_pk_fma_f32 v[26:27], v[206:207], v[26:27], v[164:165]
	s_and_b64 vcc, exec, s[44:45]
	v_lshl_add_u64 v[36:37], v[34:35], 2, s[84:85]
	s_cbranch_vccnz .LBB0_151
	global_store_dwordx4 v[36:37], v[30:33], off
	global_store_dwordx4 v[36:37], v[26:29], off offset:16
.LBB0_151:
	v_cvt_pk_bf16_f32 v38, v30, v31
	v_cvt_pk_bf16_f32 v39, v32, v33
	v_cvt_pk_bf16_f32 v40, v26, v27
	v_cvt_pk_bf16_f32 v41, v28, v29
	v_lshl_add_u64 v[42:43], v[34:35], 1, s[74:75]
	v_pk_fma_f32 v[24:25], v[204:205], v[24:25], v[178:179]
	v_pk_fma_f32 v[22:23], v[206:207], v[22:23], v[176:177]
	v_pk_fma_f32 v[20:21], v[204:205], v[20:21], v[174:175]
	s_and_b64 vcc, exec, s[44:45]
	v_pk_fma_f32 v[18:19], v[206:207], v[18:19], v[172:173]
	global_store_dwordx4 v[42:43], v[38:41], off
	s_cbranch_vccnz .LBB0_153
	global_store_dwordx4 v[36:37], v[22:25], off offset:512
	global_store_dwordx4 v[36:37], v[18:21], off offset:528

; __device__ __forceinline__ unsigned cvtpk(float lo, float hi) { f32x2_t v = {lo, hi}; bf16x2_t b = __builtin_convertvector(v, bf16x2_t); return __builtin_bit_cast(unsigned, b); }
;     __device__ __forceinline__ void operator()(const f32x4 (&acc)[2][2][4][2], const pg8::Unit& u, int wr, int wc, int fr, int fq) const {
;     ...
;             for (int m = 0; m < 4; ++m) {
;                 const int row = row0 + ai * 128 + m * 16;
;                 float sq = 0.f;
; #pragma unroll
;                 for (int bj = 0; bj < 2; ++bj) {
;                     const size_t idx = (size_t)row * DM + col0 + bj * 128;
;                     const f32x4 a0 = xa[m][bj][0], a1 = xa[m][bj][1];
;                     const f32x4 v0 = a0 + acc[ai][bj][m][0] * scale, v1 = a1 + acc[ai][bj][m][1] * scale;
;                     if (!last) { *(f32x4*)(xout + idx) = v0; *(f32x4*)(xout + idx + 4) = v1; }
;                     *(u32x4*)(xb + idx) = (u32x4){cvtpk(v0[0], v0[1]), cvtpk(v0[2], v0[3]), cvtpk(v1[0], v1[1]), cvtpk(v1[2], v1[3])};
;                     sq += (v0[0] * v0[0] + v0[1] * v0[1]) + (v0[2] * v0[2] + v0[3] * v0[3]) + (v1[0] * v1[0] + v1[1] * v1[1]) + (v1[2] * v1[2] + v1[3] * v1[3]);
;                 }
;                 sq = xrow16_sum(sq);
;                 if (fq == 0) ss[(size_t)row * 16 + u.pn * 4 + wc] = sq;
.LBB0_155:
	s_or_b64 exec, exec, s[98:99]
	v_lshlrev_b64 v[18:19], 10, v[122:123]
	v_lshl_add_u64 v[18:19], v[18:19], 0, v[212:213]
	v_mov_b32_e32 v205, v204
	s_cmp_lg_u64 s[88:89], 0
	s_cbranch_scc0 .Lres_w2_last
	s_waitcnt vmcnt(21)
	s_branch .Lres_w2_done
.Lres_w2_last:
	s_waitcnt vmcnt(9)
.Lres_w2_done:
	v_pk_fma_f32 v[16:17], v[204:205], v[16:17], v[80:81]
	v_pk_fma_f32 v[14:15], v[206:207], v[14:15], v[78:79]
	v_pk_fma_f32 v[12:13], v[204:205], v[12:13], v[76:77]
	v_pk_fma_f32 v[10:11], v[206:207], v[10:11], v[74:75]
	s_and_b64 vcc, exec, s[44:45]
	v_lshl_add_u64 v[20:21], v[18:19], 2, s[84:85]
	s_cbranch_vccnz .LBB0_157
	global_store_dwordx4 v[20:21], v[14:17], off
	global_store_dwordx4 v[20:21], v[10:13], off offset:16
.LBB0_157:
	v_cvt_pk_bf16_f32 v22, v14, v15
	v_cvt_pk_bf16_f32 v23, v16, v17
	v_cvt_pk_bf16_f32 v24, v10, v11
	v_cvt_pk_bf16_f32 v25, v12, v13
	v_lshl_add_u64 v[26:27], v[18:19], 1, s[74:75]
	v_pk_fma_f32 v[8:9], v[204:205], v[8:9], v[72:73]
	v_pk_fma_f32 v[6:7], v[206:207], v[6:7], v[70:71]
	v_pk_fma_f32 v[4:5], v[204:205], v[4:5], v[68:69]
	s_and_b64 vcc, exec, s[44:45]
	v_pk_fma_f32 v[2:3], v[206:207], v[2:3], v[66:67]
	global_store_dwordx4 v[26:27], v[22:25], off
	s_cbranch_vccnz .LBB0_159
	global_store_dwordx4 v[20:21], v[6:9], off offset:512
	global_store_dwordx4 v[20:21], v[2:5], off offset:528

.LBB0_252:
	v_mfma_f32_32x32x16_bf16 v[2:17], v[198:201], v[50:53], v[2:17]
	v_mov_b32_e32 v103, v102
	s_mov_b64 s[52:53], 0x48000
	s_add_i32 s4, s44, -2
	v_add_f32_e32 v109, v108, v109
	v_lshl_add_u64 v[106:107], v[106:107], 0, s[52:53]
	s_cmp_lt_i32 s4, s48
	v_mfma_f32_32x32x16_bf16 v[18:33], v[202:205], v[50:53], v[18:33]
	v_cvt_f32_i32_e32 v50, v122
	v_subrev_u32_e32 v122, 64, v122
	v_add_f32_e32 v51, -1.0, v50
	v_add_f32_e64 v82, v50, s24
	v_add_f32_e64 v83, v50, s25
	v_pk_add_f32 v[84:85], v[50:51], s[6:7] op_sel_hi:[0,1]
	v_mfma_f32_32x32x16_bf16 v[2:17], v[206:209], v[54:57], v[2:17]
	v_add_f32_e64 v86, v50, s38
	v_add_f32_e64 v87, v50, s39
	v_add_f32_e64 v88, v50, s16
	v_add_f32_e64 v89, v50, s17
	v_add_f32_e64 v90, v50, s62
	v_add_f32_e64 v91, v50, s63
	v_pk_add_f32 v[92:93], v[50:51], s[64:65] op_sel_hi:[0,1]
	v_and_b32_e32 v59, 0x7fffffff, v87
	v_and_b32_e32 v58, 0x7fffffff, v86
	v_and_b32_e32 v61, 0x7fffffff, v89
	v_mfma_f32_32x32x16_bf16 v[18:33], v[210:213], v[54:57], v[18:33]
	v_add_f32_e64 v94, v50, s66
	v_add_f32_e64 v95, v50, s67
	v_and_b32_e32 v55, 0x7fffffff, v83
	v_and_b32_e32 v54, 0x7fffffff, v82
	v_and_b32_e32 v57, 0x7fffffff, v85
	v_and_b32_e32 v56, 0x7fffffff, v84
	v_and_b32_e32 v60, 0x7fffffff, v88
	v_and_b32_e32 v63, 0x7fffffff, v91
	v_and_b32_e32 v62, 0x7fffffff, v90
	v_and_b32_e32 v65, 0x7fffffff, v93
	v_and_b32_e32 v64, 0x7fffffff, v92
	v_and_b32_e32 v97, 0x7fffffff, v95
	v_and_b32_e32 v96, 0x7fffffff, v94
	v_pk_fma_f32 v[110:111], v[102:103], v[54:55], v[0:1] op_sel_hi:[1,1,0]
	v_pk_fma_f32 v[54:55], v[102:103], v[56:57], v[0:1] op_sel_hi:[1,1,0]
	v_pk_fma_f32 v[56:57], v[102:103], v[58:59], v[0:1] op_sel_hi:[1,1,0]
	v_pk_fma_f32 v[58:59], v[102:103], v[60:61], v[0:1] op_sel_hi:[1,1,0]
	v_pk_fma_f32 v[60:61], v[102:103], v[62:63], v[0:1] op_sel_hi:[1,1,0]
	v_pk_fma_f32 v[62:63], v[102:103], v[64:65], v[0:1] op_sel_hi:[1,1,0]
	v_pk_fma_f32 v[64:65], v[102:103], v[96:97], v[0:1] op_sel_hi:[1,1,0]
	v_cmp_ngt_f32_e64 vcc, |v95|, s13
	v_and_b32_e32 v52, 0x7fffffff, v50
	v_and_b32_e32 v53, 0x7fffffff, v51
	v_cndmask_b32_e32 v65, v238, v65, vcc
	v_cmp_ngt_f32_e64 vcc, |v94|, s13
	v_pk_fma_f32 v[96:97], v[104:105], v[52:53], v[0:1] op_sel_hi:[1,1,0]
	s_nop 0
	v_cndmask_b32_e32 v64, v238, v64, vcc
	v_cmp_ngt_f32_e64 vcc, |v93|, s13
	s_nop 1
	v_cndmask_b32_e32 v63, v238, v63, vcc
	v_cmp_ngt_f32_e64 vcc, |v92|, s13
	s_nop 1
	v_cndmask_b32_e32 v62, v238, v62, vcc
	v_cmp_ngt_f32_e64 vcc, |v91|, s13
	s_nop 1
	v_cndmask_b32_e32 v61, v238, v61, vcc
	v_cmp_ngt_f32_e64 vcc, |v90|, s13
	s_nop 1
	v_cndmask_b32_e32 v60, v238, v60, vcc
	v_cmp_ngt_f32_e64 vcc, |v89|, s13
	s_nop 1
	v_cndmask_b32_e32 v59, v238, v59, vcc
	v_cmp_ngt_f32_e64 vcc, |v88|, s13
	s_nop 1
	v_cndmask_b32_e32 v58, v238, v58, vcc
	v_cmp_ngt_f32_e64 vcc, |v87|, s13
	s_nop 1
	v_cndmask_b32_e32 v57, v238, v57, vcc
	v_cmp_ngt_f32_e64 vcc, |v86|, s13
	s_nop 1
	v_cndmask_b32_e32 v56, v238, v56, vcc
	v_cmp_ngt_f32_e64 vcc, |v85|, s13
	s_nop 1
	v_cndmask_b32_e32 v55, v238, v55, vcc
	v_cmp_ngt_f32_e64 vcc, |v84|, s13
	s_nop 1
	v_cndmask_b32_e32 v54, v238, v54, vcc
	v_cmp_ngt_f32_e64 vcc, |v83|, s13
	s_nop 1
	v_cndmask_b32_e32 v53, v238, v111, vcc
	v_cmp_ngt_f32_e64 vcc, |v82|, s13
	s_nop 1
	v_cndmask_b32_e32 v52, v238, v110, vcc
	v_cmp_ngt_f32_e64 vcc, |v51|, s13
	s_nop 1
	v_cndmask_b32_e32 v51, v238, v97, vcc
	v_cmp_ngt_f32_e64 vcc, |v50|, s13
	s_nop 1
	v_cndmask_b32_e32 v50, v238, v96, vcc
	s_cbranch_scc0 .LBB0_248

.LBB0_259:
	s_and_b32 s2, s51, 0xc000
	s_add_i32 s4, s2, 0
	v_add_u32_e32 v0, s4, v114
	v_add_u32_e32 v82, s4, v115
	ds_read_b128 v[128:131], v0 offset:8192
	ds_read_b128 v[132:135], v82 offset:8192
	v_add_u32_e32 v0, s4, v116
	s_add_i32 s2, s4, 0x1000
	v_add_u32_e32 v82, s4, v117
	ds_read_b128 v[136:139], v0 offset:8192
	ds_read_b128 v[140:143], v82 offset:8192
	v_add_u32_e32 v0, s4, v118
	v_add_u32_e32 v90, s2, v118
	v_add_u32_e32 v92, s2, v119
	v_add_u32_e32 v94, s2, v120
	v_add_u32_e32 v96, s2, v121
	v_add_u32_e32 v108, s4, v119
	v_add_u32_e32 v112, s4, v120
	v_add_u32_e32 v113, s4, v121
	ds_read_b64_tr_b16 v[82:83], v0
	ds_read_b64_tr_b16 v[84:85], v108
	ds_read_b64_tr_b16 v[86:87], v112
	ds_read_b64_tr_b16 v[88:89], v113
	ds_read_b64_tr_b16 v[90:91], v90
	ds_read_b64_tr_b16 v[92:93], v92
	ds_read_b64_tr_b16 v[94:95], v94
	ds_read_b64_tr_b16 v[96:97], v96
	s_waitcnt lgkmcnt(0)
	v_mfma_f32_32x32x16_bf16 v[50:65], v[128:131], v[66:69], v[50:65]
	s_add_i32 s100, s51, 0x4000
	s_and_b32 s100, s100, 0xc000
	s_add_i32 s101, s4, 0x3000
	v_add_u32_e32 v176, s100, v114
	v_add_u32_e32 v177, s100, v115
	v_add_u32_e32 v178, s100, v116
	v_add_u32_e32 v179, s100, v117
	ds_read_b128 v[160:163], v176
	ds_read_b128 v[164:167], v177
	ds_read_b128 v[168:171], v178
	ds_read_b128 v[172:175], v179
	ds_read_b64_tr_b16 v[198:199], v0 offset:8192
	ds_read_b64_tr_b16 v[200:201], v108 offset:8192
	ds_read_b64_tr_b16 v[202:203], v112 offset:8192
	ds_read_b64_tr_b16 v[204:205], v113 offset:8192
	v_add_u32_e32 v180, s101, v118
	v_add_u32_e32 v181, s101, v119
	v_add_u32_e32 v182, s101, v120
	v_add_u32_e32 v183, s101, v121
	ds_read_b64_tr_b16 v[206:207], v180
	ds_read_b64_tr_b16 v[208:209], v181
	ds_read_b64_tr_b16 v[210:211], v182
	ds_read_b64_tr_b16 v[212:213], v183
	v_exp_f32_e32 v103, v34
	v_exp_f32_e32 v111, v35
	v_exp_f32_e32 v123, v36
	v_exp_f32_e32 v124, v37
	v_add_f32_e32 v110, 0, v103
	v_exp_f32_e32 v125, v38
	v_add_f32_e32 v110, v111, v110
	v_mfma_f32_32x32x16_bf16 v[50:65], v[132:135], v[70:73], v[50:65]
	v_exp_f32_e32 v126, v39
	v_add_f32_e32 v110, v123, v110
	v_exp_f32_e32 v127, v40
	v_add_f32_e32 v110, v124, v110
	v_exp_f32_e32 v128, v41
	v_add_f32_e32 v110, v125, v110
	v_exp_f32_e32 v129, v42
	v_mfma_f32_32x32x16_bf16 v[50:65], v[136:139], v[74:77], v[50:65]
	v_add_f32_e32 v110, v126, v110
	v_exp_f32_e32 v130, v43
	v_add_f32_e32 v110, v127, v110
	v_exp_f32_e32 v131, v44
	v_add_f32_e32 v110, v128, v110
	v_exp_f32_e32 v132, v45
	v_add_f32_e32 v110, v129, v110
	v_exp_f32_e32 v133, v46
	v_add_f32_e32 v110, v130, v110
	v_exp_f32_e32 v134, v47
	v_mfma_f32_32x32x16_bf16 v[50:65], v[140:143], v[78:81], v[50:65]
	v_add_f32_e32 v110, v131, v110
	v_exp_f32_e32 v135, v48
	v_add_f32_e32 v110, v132, v110
	v_exp_f32_e32 v136, v49
	v_add_f32_e32 v110, v133, v110
	v_add_f32_e32 v110, v134, v110
	v_add_f32_e32 v110, v135, v110
	v_add_f32_e32 v110, v136, v110
	v_cmp_nge_f32_e32 vcc, s12, v110
	s_cbranch_vccz .LBB0_261
	v_max_f32_e32 v103, v35, v35
	v_max_f32_e32 v110, v34, v34
	v_max_f32_e32 v103, v110, v103
	v_max3_f32 v103, v103, v36, v37
	v_max3_f32 v103, v103, v38, v39
	v_max3_f32 v103, v103, v40, v41
	v_max3_f32 v103, v103, v42, v43
	v_max3_f32 v103, v103, v44, v45
	v_max3_f32 v103, v103, v46, v47
	v_max3_f32 v103, v103, v48, v49
	ds_bpermute_b32 v110, v159, v103
	s_waitcnt lgkmcnt(0)
	v_max3_f32 v111, v103, v110, 0
	v_sub_f32_e32 v34, v34, v111
	v_exp_f32_e32 v34, v34
	v_sub_f32_e32 v35, v35, v111
	v_exp_f32_e32 v35, v35
	v_sub_f32_e32 v36, v36, v111
	v_exp_f32_e32 v36, v36
	v_sub_f32_e32 v37, v37, v111
	v_exp_f32_e32 v37, v37
	v_sub_f32_e32 v38, v38, v111
	v_add_f32_e32 v103, 0, v34
	v_exp_f32_e32 v38, v38
	v_sub_f32_e32 v39, v39, v111
	v_add_f32_e32 v103, v35, v103
	v_exp_f32_e32 v39, v39
	v_sub_f32_e32 v40, v40, v111
	v_sub_f32_e32 v41, v41, v111
	v_add_f32_e32 v103, v36, v103
	v_exp_f32_e32 v40, v40
	v_exp_f32_e32 v41, v41
	v_add_f32_e32 v103, v37, v103
	v_add_f32_e32 v103, v38, v103
	v_cvt_pk_bf16_f32 v34, v34, v35
	v_sub_f32_e32 v35, v42, v111
	v_add_f32_e32 v103, v39, v103
	v_exp_f32_e32 v123, v35
	v_cvt_pk_bf16_f32 v35, v36, v37
	v_cvt_pk_bf16_f32 v36, v38, v39
	v_sub_f32_e32 v39, v43, v111
	v_add_f32_e32 v103, v40, v103
	v_cvt_pk_bf16_f32 v37, v40, v41
	v_exp_f32_e32 v39, v39
	v_sub_f32_e32 v40, v44, v111
	v_add_f32_e32 v103, v41, v103
	v_exp_f32_e32 v40, v40
	v_sub_f32_e32 v41, v45, v111
	v_exp_f32_e32 v41, v41
	v_sub_f32_e32 v42, v46, v111
	v_add_f32_e32 v38, v123, v103
	v_exp_f32_e32 v44, v42
	v_sub_f32_e32 v42, v47, v111
	v_add_f32_e32 v38, v39, v38
	v_exp_f32_e32 v45, v42
	v_sub_f32_e32 v42, v48, v111
	v_add_f32_e32 v38, v40, v38
	v_exp_f32_e32 v46, v42
	v_sub_f32_e32 v42, v49, v111
	v_add_f32_e32 v38, v41, v38
	v_exp_f32_e32 v42, v42
	v_exp_f32_e64 v124, -v111
	v_add_f32_e32 v38, v44, v38
	v_add_f32_e32 v38, v45, v38
	v_add_f32_e32 v110, v46, v38
	v_mov_b32_e32 v43, v100
	v_sub_f32_e32 v65, v65, v111
	v_sub_f32_e32 v64, v64, v111
	v_sub_f32_e32 v63, v63, v111
	v_sub_f32_e32 v62, v62, v111
	v_sub_f32_e32 v61, v61, v111
	v_sub_f32_e32 v60, v60, v111
	v_sub_f32_e32 v59, v59, v111
	v_sub_f32_e32 v58, v58, v111
	v_sub_f32_e32 v57, v57, v111
	v_sub_f32_e32 v56, v56, v111
	v_sub_f32_e32 v55, v55, v111
	v_sub_f32_e32 v54, v54, v111
	v_sub_f32_e32 v53, v53, v111
	v_sub_f32_e32 v52, v52, v111
	v_sub_f32_e32 v51, v51, v111
	v_sub_f32_e32 v50, v50, v111
	v_pk_add_f32 v[110:111], v[42:43], v[110:111]
	v_pk_mul_f32 v[32:33], v[32:33], v[124:125] op_sel_hi:[1,0]
	v_pk_mul_f32 v[30:31], v[30:31], v[124:125] op_sel_hi:[1,0]
	v_pk_mul_f32 v[28:29], v[28:29], v[124:125] op_sel_hi:[1,0]
	v_pk_mul_f32 v[26:27], v[26:27], v[124:125] op_sel_hi:[1,0]
	v_pk_mul_f32 v[24:25], v[24:25], v[124:125] op_sel_hi:[1,0]
	v_pk_mul_f32 v[22:23], v[22:23], v[124:125] op_sel_hi:[1,0]
	v_pk_mul_f32 v[20:21], v[20:21], v[124:125] op_sel_hi:[1,0]
	v_pk_mul_f32 v[18:19], v[18:19], v[124:125] op_sel_hi:[1,0]
	v_pk_mul_f32 v[16:17], v[16:17], v[124:125] op_sel_hi:[1,0]
	v_pk_mul_f32 v[14:15], v[14:15], v[124:125] op_sel_hi:[1,0]
	v_pk_mul_f32 v[12:13], v[12:13], v[124:125] op_sel_hi:[1,0]
	v_pk_mul_f32 v[10:11], v[10:11], v[124:125] op_sel_hi:[1,0]
	v_pk_mul_f32 v[8:9], v[8:9], v[124:125] op_sel_hi:[1,0]
	v_pk_mul_f32 v[6:7], v[6:7], v[124:125] op_sel_hi:[1,0]
	v_pk_mul_f32 v[4:5], v[4:5], v[124:125] op_sel_hi:[1,0]
	v_pk_mul_f32 v[2:3], v[2:3], v[124:125] op_sel_hi:[1,0]
	v_cvt_pk_bf16_f32 v38, v123, v39
	v_cvt_pk_bf16_f32 v39, v40, v41
	v_cvt_pk_bf16_f32 v40, v44, v45
	v_cvt_pk_bf16_f32 v41, v46, v42
	v_mul_f32_e32 v109, v109, v124
	v_mov_b32_e32 v100, v111
	s_branch .LBB0_262

.LBB0_262:
	v_mfma_f32_32x32x16_bf16 v[2:17], v[82:85], v[34:37], v[2:17]
	v_mov_b32_e32 v103, v102
	s_addk_i32 s51, 0x4000
	s_and_b32 s2, s51, 0xc000
	s_add_i32 s2, s2, 0
	s_addk_i32 s4, 0x3000
	v_mfma_f32_32x32x16_bf16 v[18:33], v[86:89], v[34:37], v[18:33]
	v_add_u32_e32 v34, 32, v122
	v_cvt_f32_i32_e32 v34, v34
	v_add_f32_e32 v35, -1.0, v34
	v_add_f32_e64 v82, v34, s24
	v_add_f32_e64 v83, v34, s25
	v_mfma_f32_32x32x16_bf16 v[2:17], v[90:93], v[38:41], v[2:17]
	v_add_f32_e64 v84, v34, s6
	v_add_f32_e64 v85, v34, s7
	v_add_f32_e64 v86, v34, s38
	v_add_f32_e64 v87, v34, s39
	v_add_f32_e64 v88, v34, s16
	v_add_f32_e64 v89, v34, s17
	v_pk_add_f32 v[90:91], v[34:35], s[62:63] op_sel_hi:[0,1]
	v_pk_add_f32 v[92:93], v[34:35], s[64:65] op_sel_hi:[0,1]
	v_and_b32_e32 v43, 0x7fffffff, v87
	v_and_b32_e32 v42, 0x7fffffff, v86
	v_mfma_f32_32x32x16_bf16 v[18:33], v[94:97], v[38:41], v[18:33]
	v_add_f32_e64 v94, v34, s66
	v_add_f32_e64 v95, v34, s67
	v_and_b32_e32 v39, 0x7fffffff, v83
	v_and_b32_e32 v38, 0x7fffffff, v82
	v_and_b32_e32 v41, 0x7fffffff, v85
	v_and_b32_e32 v40, 0x7fffffff, v84
	v_and_b32_e32 v45, 0x7fffffff, v89
	v_and_b32_e32 v44, 0x7fffffff, v88
	v_and_b32_e32 v47, 0x7fffffff, v91
	v_and_b32_e32 v46, 0x7fffffff, v90
	v_and_b32_e32 v49, 0x7fffffff, v93
	v_and_b32_e32 v48, 0x7fffffff, v92
	v_and_b32_e32 v97, 0x7fffffff, v95
	v_and_b32_e32 v96, 0x7fffffff, v94
	v_pk_fma_f32 v[124:125], v[102:103], v[38:39], v[100:101] op_sel_hi:[1,1,0] neg_lo:[0,0,1] neg_hi:[0,0,1]
	v_pk_fma_f32 v[38:39], v[102:103], v[40:41], v[100:101] op_sel_hi:[1,1,0] neg_lo:[0,0,1] neg_hi:[0,0,1]
	v_pk_fma_f32 v[40:41], v[102:103], v[42:43], v[100:101] op_sel_hi:[1,1,0] neg_lo:[0,0,1] neg_hi:[0,0,1]
	v_pk_fma_f32 v[42:43], v[102:103], v[44:45], v[100:101] op_sel_hi:[1,1,0] neg_lo:[0,0,1] neg_hi:[0,0,1]
	v_pk_fma_f32 v[44:45], v[102:103], v[46:47], v[100:101] op_sel_hi:[1,1,0] neg_lo:[0,0,1] neg_hi:[0,0,1]
	v_pk_fma_f32 v[46:47], v[102:103], v[48:49], v[100:101] op_sel_hi:[1,1,0] neg_lo:[0,0,1] neg_hi:[0,0,1]
	v_pk_fma_f32 v[48:49], v[102:103], v[96:97], v[100:101] op_sel_hi:[1,1,0] neg_lo:[0,0,1] neg_hi:[0,0,1]
	v_cmp_ngt_f32_e64 vcc, |v95|, s13
	v_and_b32_e32 v36, 0x7fffffff, v34
	v_and_b32_e32 v37, 0x7fffffff, v35
	v_cndmask_b32_e32 v49, v238, v49, vcc
	v_cmp_ngt_f32_e64 vcc, |v94|, s13
	v_pk_fma_f32 v[96:97], v[104:105], v[36:37], v[100:101] op_sel_hi:[1,1,0] neg_lo:[0,0,1] neg_hi:[0,0,1]
	s_nop 0
	v_cndmask_b32_e32 v48, v238, v48, vcc
	v_cmp_ngt_f32_e64 vcc, |v93|, s13
	s_nop 1
	v_cndmask_b32_e32 v47, v238, v47, vcc
	v_cmp_ngt_f32_e64 vcc, |v92|, s13
	s_nop 1
	v_cndmask_b32_e32 v46, v238, v46, vcc
	v_cmp_ngt_f32_e64 vcc, |v91|, s13
	s_nop 1
	v_cndmask_b32_e32 v45, v238, v45, vcc
	v_cmp_ngt_f32_e64 vcc, |v90|, s13
	s_nop 1
	v_cndmask_b32_e32 v44, v238, v44, vcc
	v_cmp_ngt_f32_e64 vcc, |v89|, s13
	s_nop 1
	v_cndmask_b32_e32 v43, v238, v43, vcc
	v_cmp_ngt_f32_e64 vcc, |v88|, s13
	s_nop 1
	v_cndmask_b32_e32 v42, v238, v42, vcc
	v_cmp_ngt_f32_e64 vcc, |v87|, s13
	s_nop 1
	v_cndmask_b32_e32 v41, v238, v41, vcc
	v_cmp_ngt_f32_e64 vcc, |v86|, s13
	s_nop 1
	v_cndmask_b32_e32 v40, v238, v40, vcc
	v_cmp_ngt_f32_e64 vcc, |v85|, s13
	s_nop 1
	v_cndmask_b32_e32 v39, v238, v39, vcc
	v_cmp_ngt_f32_e64 vcc, |v84|, s13
	s_nop 1
	v_cndmask_b32_e32 v38, v238, v38, vcc
	v_cmp_ngt_f32_e64 vcc, |v83|, s13
	s_nop 1
	v_cndmask_b32_e32 v37, v238, v125, vcc
	v_cmp_ngt_f32_e64 vcc, |v82|, s13
	s_nop 0
	s_nop 0
	v_cndmask_b32_e32 v36, v238, v124, vcc
	v_cmp_ngt_f32_e64 vcc, |v35|, s13
	s_nop 0
	s_nop 0
	v_cndmask_b32_e32 v35, v238, v97, vcc
	v_cmp_ngt_f32_e64 vcc, |v34|, s13
	s_nop 0
	s_nop 0
	v_cndmask_b32_e32 v34, v238, v96, vcc
	s_nop 1
	s_waitcnt lgkmcnt(0)
	v_mfma_f32_32x32x16_bf16 v[34:49], v[160:163], v[66:69], v[34:49]
	v_exp_f32_e32 v103, v50
	v_exp_f32_e32 v111, v51
	v_exp_f32_e32 v123, v52
	v_exp_f32_e32 v124, v53
	v_add_f32_e32 v0, 0, v103
	v_exp_f32_e32 v125, v54
	v_add_f32_e32 v0, v111, v0
	v_mfma_f32_32x32x16_bf16 v[34:49], v[164:167], v[70:73], v[34:49]
	v_exp_f32_e32 v126, v55
	v_add_f32_e32 v0, v123, v0
	v_exp_f32_e32 v127, v56
	v_add_f32_e32 v0, v124, v0
	v_exp_f32_e32 v128, v57
	v_add_f32_e32 v0, v125, v0
	v_exp_f32_e32 v129, v58
	v_mfma_f32_32x32x16_bf16 v[34:49], v[168:171], v[74:77], v[34:49]
	v_add_f32_e32 v0, v126, v0
	v_exp_f32_e32 v130, v59
	v_add_f32_e32 v0, v127, v0
	v_exp_f32_e32 v131, v60
	v_add_f32_e32 v0, v128, v0
	v_exp_f32_e32 v132, v61
	v_add_f32_e32 v0, v129, v0
	v_exp_f32_e32 v133, v62
	v_mfma_f32_32x32x16_bf16 v[34:49], v[172:175], v[78:81], v[34:49]
	v_add_f32_e32 v0, v130, v0
	v_exp_f32_e32 v134, v63
	v_add_f32_e32 v0, v131, v0
	v_exp_f32_e32 v135, v64
	v_add_f32_e32 v0, v132, v0
	v_exp_f32_e32 v112, v65
	v_add_f32_e32 v0, v133, v0
	v_add_f32_e32 v0, v134, v0
	v_add_f32_e32 v108, v135, v0
	v_mov_b32_e32 v113, v110
	v_pk_add_f32 v[108:109], v[112:113], v[108:109]
	s_nop 0
	v_cmp_nge_f32_e32 vcc, s12, v108
	s_cbranch_vccnz .LBB0_251
	v_xor_b32_e32 v0, 0x80000000, v100
	v_cvt_pk_bf16_f32 v50, v103, v111
	v_cvt_pk_bf16_f32 v51, v123, v124
	v_cvt_pk_bf16_f32 v52, v125, v126
	v_cvt_pk_bf16_f32 v53, v127, v128
	v_cvt_pk_bf16_f32 v54, v129, v130
	v_cvt_pk_bf16_f32 v55, v131, v132
	v_cvt_pk_bf16_f32 v56, v133, v134
	v_cvt_pk_bf16_f32 v57, v135, v112
	s_branch .LBB0_252

; #define PG8_STAGE(bufoff, gbase, voff) do { _Pragma("unroll") for (int _i = 0; _i < 2; ++_i) \
;         __builtin_amdgcn_global_load_lds((const unsigned*)((const char*)(gbase) + (voff)[_i]), (PG8_LAS unsigned*)(lds + (bufoff) + ldsw + _i * 8192), 16, 0, 0); } while (0)
; #define PG8_LDA(dst, b, h) do { _Pragma("unroll") for (int m = 0; m < 4; ++m) _Pragma("unroll") for (int k = 0; k < 2; ++k) dst[m][k] = *(const PG8_LAS bf16x8*)(lds + PG8_SA(b, h) + aoff + m * 2048 + k * 1024); } while (0)
; #define PG8_LDB(dst, b, h) do { _Pragma("unroll") for (int n = 0; n < 2; ++n) _Pragma("unroll") for (int k = 0; k < 2; ++k) dst[n][k] = *(const PG8_LAS bf16x8*)(lds + PG8_SB(b, h) + boff + n * 2048 + k * 1024); } while (0)
; #define PG8_MMA(ai, bj, At, Bt) do { __builtin_amdgcn_s_setprio(1); _Pragma("unroll") for (int m = 0; m < 4; ++m) _Pragma("unroll") for (int n = 0; n < 2; ++n) _Pragma("unroll") for (int k = 0; k < 2; ++k) \
;         acc[ai][bj][m][n] = __builtin_amdgcn_mfma_f32_16x16x32_bf16(Bt[n][k], At[m][k], acc[ai][bj][m][n], 0, 0, 0); __builtin_amdgcn_s_setprio(0); } while (0)
; #define PG8_WAIT_V(n) asm volatile("s_waitcnt vmcnt(" #n ")" ::: "memory")
; #define PG8_WAIT_L(n) asm volatile("s_waitcnt lgkmcnt(" #n ")" ::: "memory")
; #define PG8_BAR __builtin_amdgcn_s_barrier()
; #define PG8_SCHED __builtin_amdgcn_sched_barrier(0)
; template <class Epi, class Sched, bool ALIGN_EPI = false, bool SP2 = false>
; __device__ __forceinline__ void gemm_phase(PG8_LAS unsigned char* lds, const Gemm g, const Sched& S, const Epi& E) {
;     ...
;             PG8_LDB(B0, 0, 0); PG8_LDB(B1, 0, 1); PG8_SCHED; PG8_LDA(At, 0, 0); PG8_STAGE(PG8_SA(1, 1), a1 + hstep, voffA);
;             PG8_WAIT_V(8); PG8_WAIT_L(0); PG8_BAR; PG8_MMA(0, 0, At, B0); PG8_MMA(0, 1, At, B1); PG8_BAR; PG8_SCHED;
;             PG8_LDA(At, 0, 1); PG8_STAGE(PG8_SB(0, 0), b2, voffB); PG8_STAGE(PG8_SB(0, 1), b2 + hstep, voffB); PG8_STAGE(PG8_SA(0, 0), a2, voffA);
;             PG8_WAIT_V(8); PG8_WAIT_L(0); PG8_BAR; PG8_MMA(1, 0, At, B0); PG8_MMA(1, 1, At, B1); PG8_BAR; PG8_SCHED;
.LBB0_275:
	s_add_u32 s78, s84, 0xfffc0080
	s_addc_u32 s79, s85, -1
	s_add_i32 s94, 0, 0x10000
	s_cmp_eq_u32 s93, 12
	s_cselect_b32 s89, s53, s79
	s_cselect_b32 s88, s77, s78
	v_add_u32_e32 v146, s94, v151
	s_cselect_b32 s87, s51, s92
	s_cselect_b32 s86, s90, s91
	s_add_i32 s78, 0, 0x14000
	ds_read_b128 v[142:145], v146
	ds_read_b128 v[160:163], v146 offset:1024
	ds_read_b128 v[164:167], v146 offset:2048
	ds_read_b128 v[168:171], v146 offset:3072
	v_add_u32_e32 v146, s78, v151
	ds_read_b128 v[172:175], v146
	ds_read_b128 v[176:179], v146 offset:1024
	ds_read_b128 v[180:183], v146 offset:2048
	ds_read_b128 v[198:201], v146 offset:3072
	v_lshl_add_u64 v[148:149], s[84:85], 0, v[138:139]
	s_add_i32 m0, s18, 0xc000
	ds_read_b128 v[202:205], v159
	ds_read_b128 v[206:209], v159 offset:1024
	ds_read_b128 v[210:213], v159 offset:2048
	ds_read_b128 v[214:217], v159 offset:3072
	ds_read_b128 v[218:221], v159 offset:4096
	ds_read_b128 v[222:225], v159 offset:5120
	ds_read_b128 v[240:243], v159 offset:6144
	ds_read_b128 v[244:247], v159 offset:7168
	global_load_lds_dwordx4 v[148:149], off
	v_lshl_add_u64 v[148:149], s[84:85], 0, v[140:141]
	s_add_i32 m0, s18, 0xe000
	s_nop 0
	global_load_lds_dwordx4 v[148:149], off
	s_waitcnt vmcnt(8)
	s_and_b64 vcc, exec, s[48:49]
	s_cbranch_vccnz .Lgu_lead0
	s_waitcnt lgkmcnt(0)
.Lgu_lead0:
	s_barrier
	s_setprio 1
	s_waitcnt lgkmcnt(0)
	v_mfma_f32_16x16x32_bf16 v[126:129], v[142:145], v[202:205], v[126:129]
	v_mfma_f32_16x16x32_bf16 v[122:125], v[164:167], v[202:205], v[122:125]
	v_mfma_f32_16x16x32_bf16 v[110:113], v[142:145], v[210:213], v[110:113]
	v_mfma_f32_16x16x32_bf16 v[106:109], v[164:167], v[210:213], v[106:109]
	v_mfma_f32_16x16x32_bf16 v[94:97], v[142:145], v[218:221], v[94:97]
	v_mfma_f32_16x16x32_bf16 v[90:93], v[164:167], v[218:221], v[90:93]
	v_mfma_f32_16x16x32_bf16 v[78:81], v[142:145], v[240:243], v[78:81]
	v_mfma_f32_16x16x32_bf16 v[74:77], v[164:167], v[240:243], v[74:77]
	v_mfma_f32_16x16x32_bf16 v[126:129], v[160:163], v[206:209], v[126:129]
	v_mfma_f32_16x16x32_bf16 v[122:125], v[168:171], v[206:209], v[122:125]
	v_mfma_f32_16x16x32_bf16 v[110:113], v[160:163], v[214:217], v[110:113]
	v_mfma_f32_16x16x32_bf16 v[106:109], v[168:171], v[214:217], v[106:109]
	v_mfma_f32_16x16x32_bf16 v[94:97], v[160:163], v[222:225], v[94:97]
	v_mfma_f32_16x16x32_bf16 v[90:93], v[168:171], v[222:225], v[90:93]
	v_mfma_f32_16x16x32_bf16 v[78:81], v[160:163], v[244:247], v[78:81]
	v_mfma_f32_16x16x32_bf16 v[74:77], v[168:171], v[244:247], v[74:77]
	s_setprio 0
	s_setprio 1
	v_mfma_f32_16x16x32_bf16 v[118:121], v[172:175], v[202:205], v[118:121]
	v_mfma_f32_16x16x32_bf16 v[114:117], v[180:183], v[202:205], v[114:117]
	v_mfma_f32_16x16x32_bf16 v[102:105], v[172:175], v[210:213], v[102:105]
	v_mfma_f32_16x16x32_bf16 v[98:101], v[180:183], v[210:213], v[98:101]
	v_mfma_f32_16x16x32_bf16 v[86:89], v[172:175], v[218:221], v[86:89]
	v_mfma_f32_16x16x32_bf16 v[82:85], v[180:183], v[218:221], v[82:85]
	v_mfma_f32_16x16x32_bf16 v[70:73], v[172:175], v[240:243], v[70:73]
	v_mfma_f32_16x16x32_bf16 v[66:69], v[180:183], v[240:243], v[66:69]
	v_mfma_f32_16x16x32_bf16 v[118:121], v[176:179], v[206:209], v[118:121]
	v_mfma_f32_16x16x32_bf16 v[114:117], v[198:201], v[206:209], v[114:117]
	v_mfma_f32_16x16x32_bf16 v[102:105], v[176:179], v[214:217], v[102:105]
	v_mfma_f32_16x16x32_bf16 v[98:101], v[198:201], v[214:217], v[98:101]
	v_mfma_f32_16x16x32_bf16 v[86:89], v[176:179], v[222:225], v[86:89]
	v_mfma_f32_16x16x32_bf16 v[82:85], v[198:201], v[222:225], v[82:85]
	v_mfma_f32_16x16x32_bf16 v[70:73], v[176:179], v[244:247], v[70:73]
	v_mfma_f32_16x16x32_bf16 v[66:69], v[198:201], v[244:247], v[66:69]
	s_setprio 0
	s_barrier
	s_add_i32 s79, s94, s9
	v_lshl_add_u64 v[148:149], s[86:87], 0, v[0:1]
	s_mov_b32 m0, s79
	ds_read_b128 v[202:205], v159 offset:16384
	ds_read_b128 v[206:209], v159 offset:17408
	ds_read_b128 v[210:213], v159 offset:18432
	ds_read_b128 v[214:217], v159 offset:19456
	ds_read_b128 v[218:221], v159 offset:20480
	ds_read_b128 v[222:225], v159 offset:21504
	ds_read_b128 v[240:243], v159 offset:22528
	ds_read_b128 v[244:247], v159 offset:23552
	global_load_lds_dwordx4 v[148:149], off
	s_add_i32 m0, s79, 0x2000
	s_add_u32 s94, s86, 0x40000
	v_lshl_add_u64 v[152:153], s[86:87], 0, v[130:131]
	s_addc_u32 s95, s87, 0
	s_add_i32 s78, s78, s9
	global_load_lds_dwordx4 v[152:153], off
	v_lshl_add_u64 v[156:157], s[94:95], 0, v[0:1]
	s_mov_b32 m0, s78
	v_lshl_add_u64 v[184:185], s[88:89], 0, v[132:133]
	global_load_lds_dwordx4 v[156:157], off
	v_lshl_add_u64 v[156:157], s[94:95], 0, v[130:131]
	s_add_i32 m0, s78, 0x2000
	s_nop 0
	global_load_lds_dwordx4 v[156:157], off
	v_lshl_add_u64 v[156:157], s[88:89], 0, v[134:135]
	s_mov_b32 m0, s18
	s_nop 0
	global_load_lds_dwordx4 v[156:157], off
	s_mov_b32 m0, s58
	s_nop 0
	global_load_lds_dwordx4 v[184:185], off
	s_waitcnt vmcnt(8)
	s_and_b64 vcc, exec, s[48:49]
	s_cbranch_vccnz .Lgu_lead1
	s_waitcnt lgkmcnt(0)
; #define PG8_STAGE(bufoff, gbase, voff) do { _Pragma("unroll") for (int _i = 0; _i < 2; ++_i) \
;         __builtin_amdgcn_global_load_lds((const unsigned*)((const char*)(gbase) + (voff)[_i]), (PG8_LAS unsigned*)(lds + (bufoff) + ldsw + _i * 8192), 16, 0, 0); } while (0)
; #define PG8_LDA(dst, b, h) do { _Pragma("unroll") for (int m = 0; m < 4; ++m) _Pragma("unroll") for (int k = 0; k < 2; ++k) dst[m][k] = *(const PG8_LAS bf16x8*)(lds + PG8_SA(b, h) + aoff + m * 2048 + k * 1024); } while (0)
; #define PG8_LDB(dst, b, h) do { _Pragma("unroll") for (int n = 0; n < 2; ++n) _Pragma("unroll") for (int k = 0; k < 2; ++k) dst[n][k] = *(const PG8_LAS bf16x8*)(lds + PG8_SB(b, h) + boff + n * 2048 + k * 1024); } while (0)
; #define PG8_MMA(ai, bj, At, Bt) do { __builtin_amdgcn_s_setprio(1); _Pragma("unroll") for (int m = 0; m < 4; ++m) _Pragma("unroll") for (int n = 0; n < 2; ++n) _Pragma("unroll") for (int k = 0; k < 2; ++k) \
;         acc[ai][bj][m][n] = __builtin_amdgcn_mfma_f32_16x16x32_bf16(Bt[n][k], At[m][k], acc[ai][bj][m][n], 0, 0, 0); __builtin_amdgcn_s_setprio(0); } while (0)
; #define PG8_WAIT_V(n) asm volatile("s_waitcnt vmcnt(" #n ")" ::: "memory")
; #define PG8_WAIT_L(n) asm volatile("s_waitcnt lgkmcnt(" #n ")" ::: "memory")
; #define PG8_BAR __builtin_amdgcn_s_barrier()
; #define PG8_SCHED __builtin_amdgcn_sched_barrier(0)
; template <class Epi, class Sched, bool ALIGN_EPI = false, bool SP2 = false>
; __device__ __forceinline__ void gemm_phase(PG8_LAS unsigned char* lds, const Gemm g, const Sched& S, const Epi& E) {
;     ...
;             PG8_WAIT_V(8); PG8_WAIT_L(0); PG8_BAR; PG8_MMA(0, 0, At, B0); PG8_MMA(0, 1, At, B1); PG8_BAR; PG8_SCHED;
;             PG8_LDA(At, 0, 1); PG8_STAGE(PG8_SB(0, 0), b2, voffB); PG8_STAGE(PG8_SB(0, 1), b2 + hstep, voffB); PG8_STAGE(PG8_SA(0, 0), a2, voffA);
;             PG8_WAIT_V(8); PG8_WAIT_L(0); PG8_BAR; PG8_MMA(1, 0, At, B0); PG8_MMA(1, 1, At, B1); PG8_BAR; PG8_SCHED;
;             PG8_LDB(B0, 1, 0); PG8_LDB(B1, 1, 1); PG8_SCHED; PG8_LDA(At, 1, 0); PG8_STAGE(PG8_SA(0, 1), a2 + hstep, voffA);
;             PG8_WAIT_V(8); PG8_WAIT_L(0); PG8_BAR; PG8_MMA(0, 0, At, B0); PG8_MMA(0, 1, At, B1); PG8_BAR; PG8_SCHED;
.Lgu_lead1:
	s_barrier
	s_setprio 1
	s_waitcnt lgkmcnt(0)
	v_mfma_f32_16x16x32_bf16 v[62:65], v[142:145], v[202:205], v[62:65]
	v_mfma_f32_16x16x32_bf16 v[58:61], v[164:167], v[202:205], v[58:61]
	v_mfma_f32_16x16x32_bf16 v[46:49], v[142:145], v[210:213], v[46:49]
	v_mfma_f32_16x16x32_bf16 v[42:45], v[164:167], v[210:213], v[42:45]
	v_mfma_f32_16x16x32_bf16 v[30:33], v[142:145], v[218:221], v[30:33]
	v_mfma_f32_16x16x32_bf16 v[26:29], v[164:167], v[218:221], v[26:29]
	v_mfma_f32_16x16x32_bf16 v[14:17], v[142:145], v[240:243], v[14:17]
	v_mfma_f32_16x16x32_bf16 v[10:13], v[164:167], v[240:243], v[10:13]
	v_mfma_f32_16x16x32_bf16 v[62:65], v[160:163], v[206:209], v[62:65]
	v_mfma_f32_16x16x32_bf16 v[58:61], v[168:171], v[206:209], v[58:61]
	v_mfma_f32_16x16x32_bf16 v[46:49], v[160:163], v[214:217], v[46:49]
	v_mfma_f32_16x16x32_bf16 v[42:45], v[168:171], v[214:217], v[42:45]
	v_mfma_f32_16x16x32_bf16 v[30:33], v[160:163], v[222:225], v[30:33]
	v_mfma_f32_16x16x32_bf16 v[26:29], v[168:171], v[222:225], v[26:29]
	v_mfma_f32_16x16x32_bf16 v[14:17], v[160:163], v[244:247], v[14:17]
	v_mfma_f32_16x16x32_bf16 v[10:13], v[168:171], v[244:247], v[10:13]
	s_setprio 0
	s_setprio 1
	v_mfma_f32_16x16x32_bf16 v[54:57], v[172:175], v[202:205], v[54:57]
	v_mfma_f32_16x16x32_bf16 v[50:53], v[180:183], v[202:205], v[50:53]
	v_mfma_f32_16x16x32_bf16 v[38:41], v[172:175], v[210:213], v[38:41]
	v_mfma_f32_16x16x32_bf16 v[34:37], v[180:183], v[210:213], v[34:37]
	v_mfma_f32_16x16x32_bf16 v[22:25], v[172:175], v[218:221], v[22:25]
	v_mfma_f32_16x16x32_bf16 v[18:21], v[180:183], v[218:221], v[18:21]
	v_mfma_f32_16x16x32_bf16 v[6:9], v[172:175], v[240:243], v[6:9]
	v_mfma_f32_16x16x32_bf16 v[2:5], v[180:183], v[240:243], v[2:5]
	v_mfma_f32_16x16x32_bf16 v[54:57], v[176:179], v[206:209], v[54:57]
	v_mfma_f32_16x16x32_bf16 v[50:53], v[198:201], v[206:209], v[50:53]
	v_mfma_f32_16x16x32_bf16 v[38:41], v[176:179], v[214:217], v[38:41]
	v_mfma_f32_16x16x32_bf16 v[34:37], v[198:201], v[214:217], v[34:37]
	v_mfma_f32_16x16x32_bf16 v[22:25], v[176:179], v[222:225], v[22:25]
	v_mfma_f32_16x16x32_bf16 v[18:21], v[198:201], v[222:225], v[18:21]
	v_mfma_f32_16x16x32_bf16 v[6:9], v[176:179], v[244:247], v[6:9]
	v_mfma_f32_16x16x32_bf16 v[2:5], v[198:201], v[244:247], v[2:5]
	s_setprio 0
	s_barrier
	s_add_i32 s78, 0, 0x18000
	v_add_u32_e32 v146, s78, v151
	s_add_i32 s79, 0, 0x1c000
	ds_read_b128 v[142:145], v146
	ds_read_b128 v[160:163], v146 offset:1024
	ds_read_b128 v[164:167], v146 offset:2048
	ds_read_b128 v[168:171], v146 offset:3072
	v_add_u32_e32 v146, s79, v151
	ds_read_b128 v[172:175], v146
	ds_read_b128 v[176:179], v146 offset:1024
	ds_read_b128 v[180:183], v146 offset:2048
	ds_read_b128 v[198:201], v146 offset:3072
	s_add_u32 s88, s88, 0x40000
	s_addc_u32 s89, s89, 0
	s_mov_b32 m0, s59
	v_lshl_add_u64 v[226:227], s[88:89], 0, v[134:135]
	ds_read_b128 v[202:205], v159 offset:32768
	ds_read_b128 v[206:209], v159 offset:33792
	ds_read_b128 v[210:213], v159 offset:34816
	ds_read_b128 v[214:217], v159 offset:35840
	ds_read_b128 v[218:221], v159 offset:36864
	ds_read_b128 v[222:225], v159 offset:37888
	ds_read_b128 v[240:243], v159 offset:38912
	ds_read_b128 v[244:247], v159 offset:39936
	global_load_lds_dwordx4 v[226:227], off
	v_lshl_add_u64 v[226:227], s[88:89], 0, v[132:133]
	s_mov_b32 m0, s60
	s_nop 0
	global_load_lds_dwordx4 v[226:227], off
	s_waitcnt vmcnt(8)
	s_and_b64 vcc, exec, s[48:49]
	s_cbranch_vccnz .Lgu_lead2
	s_waitcnt lgkmcnt(0)
.Lgu_lead2:
	s_barrier
	s_setprio 1
	s_waitcnt lgkmcnt(0)
	v_mfma_f32_16x16x32_bf16 v[126:129], v[142:145], v[202:205], v[126:129]
	v_mfma_f32_16x16x32_bf16 v[122:125], v[164:167], v[202:205], v[122:125]
	v_mfma_f32_16x16x32_bf16 v[110:113], v[142:145], v[210:213], v[110:113]
	v_mfma_f32_16x16x32_bf16 v[106:109], v[164:167], v[210:213], v[106:109]
	v_mfma_f32_16x16x32_bf16 v[94:97], v[142:145], v[218:221], v[94:97]
	v_mfma_f32_16x16x32_bf16 v[90:93], v[164:167], v[218:221], v[90:93]
	v_mfma_f32_16x16x32_bf16 v[78:81], v[142:145], v[240:243], v[78:81]
	v_mfma_f32_16x16x32_bf16 v[74:77], v[164:167], v[240:243], v[74:77]
	v_mfma_f32_16x16x32_bf16 v[126:129], v[160:163], v[206:209], v[126:129]
	v_mfma_f32_16x16x32_bf16 v[122:125], v[168:171], v[206:209], v[122:125]
	v_mfma_f32_16x16x32_bf16 v[110:113], v[160:163], v[214:217], v[110:113]
	v_mfma_f32_16x16x32_bf16 v[106:109], v[168:171], v[214:217], v[106:109]
	v_mfma_f32_16x16x32_bf16 v[94:97], v[160:163], v[222:225], v[94:97]
	v_mfma_f32_16x16x32_bf16 v[90:93], v[168:171], v[222:225], v[90:93]
	v_mfma_f32_16x16x32_bf16 v[78:81], v[160:163], v[244:247], v[78:81]
	v_mfma_f32_16x16x32_bf16 v[74:77], v[168:171], v[244:247], v[74:77]
	s_setprio 0
	s_setprio 1
	v_mfma_f32_16x16x32_bf16 v[118:121], v[172:175], v[202:205], v[118:121]
	v_mfma_f32_16x16x32_bf16 v[114:117], v[180:183], v[202:205], v[114:117]
	v_mfma_f32_16x16x32_bf16 v[102:105], v[172:175], v[210:213], v[102:105]
	v_mfma_f32_16x16x32_bf16 v[98:101], v[180:183], v[210:213], v[98:101]
	v_mfma_f32_16x16x32_bf16 v[86:89], v[172:175], v[218:221], v[86:89]
	v_mfma_f32_16x16x32_bf16 v[82:85], v[180:183], v[218:221], v[82:85]
	v_mfma_f32_16x16x32_bf16 v[70:73], v[172:175], v[240:243], v[70:73]
	v_mfma_f32_16x16x32_bf16 v[66:69], v[180:183], v[240:243], v[66:69]
	v_mfma_f32_16x16x32_bf16 v[118:121], v[176:179], v[206:209], v[118:121]
	v_mfma_f32_16x16x32_bf16 v[114:117], v[198:201], v[206:209], v[114:117]
	v_mfma_f32_16x16x32_bf16 v[102:105], v[176:179], v[214:217], v[102:105]
	v_mfma_f32_16x16x32_bf16 v[98:101], v[198:201], v[214:217], v[98:101]
	v_mfma_f32_16x16x32_bf16 v[86:89], v[176:179], v[222:225], v[86:89]
	v_mfma_f32_16x16x32_bf16 v[82:85], v[198:201], v[222:225], v[82:85]
	v_mfma_f32_16x16x32_bf16 v[70:73], v[176:179], v[244:247], v[70:73]
	v_mfma_f32_16x16x32_bf16 v[66:69], v[198:201], v[244:247], v[66:69]
	s_setprio 0
	s_barrier
; #define PG8_STAGE(bufoff, gbase, voff) do { _Pragma("unroll") for (int _i = 0; _i < 2; ++_i) \
;         __builtin_amdgcn_global_load_lds((const unsigned*)((const char*)(gbase) + (voff)[_i]), (PG8_LAS unsigned*)(lds + (bufoff) + ldsw + _i * 8192), 16, 0, 0); } while (0)
; #define PG8_LDA(dst, b, h) do { _Pragma("unroll") for (int m = 0; m < 4; ++m) _Pragma("unroll") for (int k = 0; k < 2; ++k) dst[m][k] = *(const PG8_LAS bf16x8*)(lds + PG8_SA(b, h) + aoff + m * 2048 + k * 1024); } while (0)
; #define PG8_MMA(ai, bj, At, Bt) do { __builtin_amdgcn_s_setprio(1); _Pragma("unroll") for (int m = 0; m < 4; ++m) _Pragma("unroll") for (int n = 0; n < 2; ++n) _Pragma("unroll") for (int k = 0; k < 2; ++k) \
;         acc[ai][bj][m][n] = __builtin_amdgcn_mfma_f32_16x16x32_bf16(Bt[n][k], At[m][k], acc[ai][bj][m][n], 0, 0, 0); __builtin_amdgcn_s_setprio(0); } while (0)
; #define PG8_WAIT_V(n) asm volatile("s_waitcnt vmcnt(" #n ")" ::: "memory")
; #define PG8_WAIT_L(n) asm volatile("s_waitcnt lgkmcnt(" #n ")" ::: "memory")
; #define PG8_BAR __builtin_amdgcn_s_barrier()
; #define PG8_SCHED __builtin_amdgcn_sched_barrier(0)
; template <class Epi, class Sched, bool ALIGN_EPI = false, bool SP2 = false>
; __device__ __forceinline__ void gemm_phase(PG8_LAS unsigned char* lds, const Gemm g, const Sched& S, const Epi& E) {
;     ...
;             PG8_WAIT_V(8); PG8_WAIT_L(0); PG8_BAR; PG8_MMA(0, 0, At, B0); PG8_MMA(0, 1, At, B1); PG8_BAR; PG8_SCHED;
;             PG8_LDA(At, 1, 1); PG8_STAGE(PG8_SB(1, 0), b3, voffB); PG8_STAGE(PG8_SB(1, 1), b3 + hstep, voffB); PG8_STAGE(PG8_SA(1, 0), a3, voffA);
;             PG8_WAIT_V(8); PG8_WAIT_L(0); PG8_BAR; PG8_MMA(1, 0, At, B0); PG8_MMA(1, 1, At, B1); PG8_BAR; PG8_SCHED;
; __device__ __forceinline__ void rows_rstd(const float* __restrict__ ss, int row0, int fq, float (&r)[8]) {
;     f32x4 v[8];
; #pragma unroll
;     for (int i = 0; i < 8; ++i) v[i] = *(const f32x4*)(ss + (size_t)(row0 + (i >> 2) * 128 + (i & 3) * 16) * 16 + 4 * fq);
; #pragma unroll
	s_add_i32 s78, s78, s9
	v_lshl_add_u64 v[148:149], v[148:149], 0, s[20:21]
	s_mov_b32 m0, s78
	ds_read_b128 v[202:205], v159 offset:49152
	ds_read_b128 v[206:209], v159 offset:50176
	ds_read_b128 v[210:213], v159 offset:51200
	ds_read_b128 v[214:217], v159 offset:52224
	ds_read_b128 v[218:221], v159 offset:53248
	ds_read_b128 v[222:225], v159 offset:54272
	ds_read_b128 v[240:243], v159 offset:55296
	ds_read_b128 v[244:247], v159 offset:56320
	global_load_lds_dwordx4 v[148:149], off
	s_add_i32 m0, s78, 0x2000
	s_add_u32 s86, s86, 0x40080
	v_lshl_add_u64 v[148:149], v[152:153], 0, s[20:21]
	s_addc_u32 s87, s87, 0
	s_add_i32 s78, s79, s9
	global_load_lds_dwordx4 v[148:149], off
	v_lshl_add_u64 v[148:149], s[86:87], 0, v[0:1]
	s_mov_b32 m0, s78
	s_nop 0
	global_load_lds_dwordx4 v[148:149], off
	v_lshl_add_u64 v[148:149], s[86:87], 0, v[130:131]
	s_add_i32 m0, s78, 0x2000
	s_nop 0
	global_load_lds_dwordx4 v[148:149], off
	v_lshl_add_u64 v[148:149], v[156:157], 0, s[20:21]
	s_mov_b32 m0, s61
	s_nop 0
	global_load_lds_dwordx4 v[148:149], off
	v_lshl_add_u64 v[148:149], v[184:185], 0, s[20:21]
	s_mov_b32 m0, s70
	s_nop 0
	global_load_lds_dwordx4 v[148:149], off
	s_waitcnt vmcnt(8)
	s_and_b64 vcc, exec, s[48:49]
	s_cbranch_vccnz .Lgu_lead3
	s_waitcnt lgkmcnt(0)
.Lgu_lead3:
	s_barrier
	s_setprio 1
	s_waitcnt lgkmcnt(0)
	v_mfma_f32_16x16x32_bf16 v[62:65], v[142:145], v[202:205], v[62:65]
	v_mfma_f32_16x16x32_bf16 v[58:61], v[164:167], v[202:205], v[58:61]
	v_mfma_f32_16x16x32_bf16 v[46:49], v[142:145], v[210:213], v[46:49]
	v_mfma_f32_16x16x32_bf16 v[42:45], v[164:167], v[210:213], v[42:45]
	v_mfma_f32_16x16x32_bf16 v[30:33], v[142:145], v[218:221], v[30:33]
	v_mfma_f32_16x16x32_bf16 v[26:29], v[164:167], v[218:221], v[26:29]
	v_mfma_f32_16x16x32_bf16 v[14:17], v[142:145], v[240:243], v[14:17]
	v_mfma_f32_16x16x32_bf16 v[10:13], v[164:167], v[240:243], v[10:13]
	v_mfma_f32_16x16x32_bf16 v[62:65], v[160:163], v[206:209], v[62:65]
	v_mfma_f32_16x16x32_bf16 v[58:61], v[168:171], v[206:209], v[58:61]
	v_mfma_f32_16x16x32_bf16 v[46:49], v[160:163], v[214:217], v[46:49]
	v_mfma_f32_16x16x32_bf16 v[42:45], v[168:171], v[214:217], v[42:45]
	v_mfma_f32_16x16x32_bf16 v[30:33], v[160:163], v[222:225], v[30:33]
	v_mfma_f32_16x16x32_bf16 v[26:29], v[168:171], v[222:225], v[26:29]
	v_mfma_f32_16x16x32_bf16 v[14:17], v[160:163], v[244:247], v[14:17]
	v_mfma_f32_16x16x32_bf16 v[10:13], v[168:171], v[244:247], v[10:13]
	s_setprio 0
	s_setprio 1
	v_mfma_f32_16x16x32_bf16 v[54:57], v[172:175], v[202:205], v[54:57]
	v_mfma_f32_16x16x32_bf16 v[50:53], v[180:183], v[202:205], v[50:53]
	v_mfma_f32_16x16x32_bf16 v[38:41], v[172:175], v[210:213], v[38:41]
	v_mfma_f32_16x16x32_bf16 v[34:37], v[180:183], v[210:213], v[34:37]
	v_mfma_f32_16x16x32_bf16 v[22:25], v[172:175], v[218:221], v[22:25]
	v_mfma_f32_16x16x32_bf16 v[18:21], v[180:183], v[218:221], v[18:21]
	v_mfma_f32_16x16x32_bf16 v[6:9], v[172:175], v[240:243], v[6:9]
	v_mfma_f32_16x16x32_bf16 v[2:5], v[180:183], v[240:243], v[2:5]
	v_mfma_f32_16x16x32_bf16 v[54:57], v[176:179], v[206:209], v[54:57]
	v_mfma_f32_16x16x32_bf16 v[50:53], v[198:201], v[206:209], v[50:53]
	v_mfma_f32_16x16x32_bf16 v[38:41], v[176:179], v[214:217], v[38:41]
	v_mfma_f32_16x16x32_bf16 v[34:37], v[198:201], v[214:217], v[34:37]
	v_mfma_f32_16x16x32_bf16 v[22:25], v[176:179], v[222:225], v[22:25]
	v_mfma_f32_16x16x32_bf16 v[18:21], v[198:201], v[222:225], v[18:21]
	v_mfma_f32_16x16x32_bf16 v[6:9], v[176:179], v[244:247], v[6:9]
	v_mfma_f32_16x16x32_bf16 v[2:5], v[198:201], v[244:247], v[2:5]
	s_setprio 0
	s_barrier
	s_add_i32 s93, s93, 2
	s_add_u32 s84, s84, 0x100
	s_addc_u32 s85, s85, 0
	s_add_u32 s91, s91, 0x100
	s_addc_u32 s92, s92, 0
	s_cmp_gt_u32 s93, 13
	s_cbranch_scc0 .LBB0_275
.LBB0_278:
	v_lshl_add_u32 v168, s4, 8, v147
	v_or_b32_e32 v164, 16, v168
	v_ashrrev_i32_e32 v169, 31, v168
	v_ashrrev_i32_e32 v165, 31, v164
	v_lshlrev_b64 v[142:143], 6, v[168:169]
	v_lshlrev_b64 v[144:145], 6, v[164:165]
	v_or_b32_e32 v160, 32, v168
	v_or_b32_e32 v156, 48, v168
	v_lshl_add_u64 v[142:143], v[136:137], 0, v[142:143]
	v_lshl_add_u64 v[144:145], v[136:137], 0, v[144:145]
	v_ashrrev_i32_e32 v161, 31, v160
	v_ashrrev_i32_e32 v157, 31, v156
	global_load_dwordx4 v[170:173], v[142:143], off
	global_load_dwordx4 v[174:177], v[144:145], off
	v_lshlrev_b64 v[142:143], 6, v[160:161]
	v_lshlrev_b64 v[144:145], 6, v[156:157]
	v_add_u32_e32 v152, 0x80, v168
	v_add_u32_e32 v148, 0x90, v168
	v_lshl_add_u64 v[142:143], v[136:137], 0, v[142:143]
	v_lshl_add_u64 v[144:145], v[136:137], 0, v[144:145]
	v_ashrrev_i32_e32 v153, 31, v152
	v_ashrrev_i32_e32 v149, 31, v148
	global_load_dwordx4 v[178:181], v[142:143], off
	global_load_dwordx4 v[182:185], v[144:145], off
	v_lshlrev_b64 v[142:143], 6, v[152:153]
	v_lshlrev_b64 v[144:145], 6, v[148:149]
	v_lshl_add_u64 v[142:143], v[136:137], 0, v[142:143]
	v_lshl_add_u64 v[144:145], v[136:137], 0, v[144:145]
	global_load_dwordx4 v[198:201], v[142:143], off
	global_load_dwordx4 v[202:205], v[144:145], off
	v_add_u32_e32 v144, 0xa0, v168
	v_ashrrev_i32_e32 v145, 31, v144
	v_lshlrev_b64 v[142:143], 6, v[144:145]
	v_lshl_add_u64 v[142:143], v[136:137], 0, v[142:143]
	global_load_dwordx4 v[206:209], v[142:143], off
	v_add_u32_e32 v142, 0xb0, v168
	v_ashrrev_i32_e32 v143, 31, v142
	v_lshlrev_b64 v[162:163], 6, v[142:143]
	v_lshl_add_u64 v[162:163], v[136:137], 0, v[162:163]
	global_load_dwordx4 v[210:213], v[162:163], off
	s_and_b64 vcc, exec, s[48:49]
	s_cbranch_vccz .Lgu_epi_nobar
	s_barrier
; __device__ __forceinline__ unsigned cvtpk(float lo, float hi) { f32x2_t v = {lo, hi}; bf16x2_t b = __builtin_convertvector(v, bf16x2_t); return __builtin_bit_cast(unsigned, b); }
; __device__ __forceinline__ void rows_rstd(const float* __restrict__ ss, int row0, int fq, float (&r)[8]) {
;     ...
;     for (int i = 0; i < 8; ++i) r[i] = (v[i][0] + v[i][1]) + (v[i][2] + v[i][3]);
; #pragma unroll
;     for (int i = 0; i < 8; ++i) r[i] = xrow16_sum(r[i]);
; #pragma unroll
;     for (int i = 0; i < 8; ++i) r[i] = __builtin_amdgcn_rsqf(r[i] * (1.0f / DM) + RMS_EPS);
; }
;     __device__ __forceinline__ void operator()(const f32x4 (&acc)[2][2][4][2], const pg8::Unit& u, int wr, int wc, int fr, int fq) const {
;         const int row0 = u.pm * 256 + wr * 64 + fr, col0 = u.pn * 128 + wc * 32 + 8 * fq;
;         float rr[8]; rows_rstd(ss, row0, fq, rr);
; #pragma unroll
;         for (int ai = 0; ai < 2; ++ai)
; #pragma unroll
;             for (int m = 0; m < 4; ++m) {
;                 const int row = row0 + ai * 128 + m * 16;
;                 const float r = rr[ai * 4 + m];
;                 unsigned o[4];
; #pragma unroll
;                 for (int n = 0; n < 2; ++n) {
;                     float hv[4];
; #pragma unroll
;                     for (int i = 0; i < 4; ++i) {
;                         const float g = acc[ai][0][m][n][i] * r, up = acc[ai][1][m][n][i] * r;
;                         const float sg = g * __builtin_amdgcn_rcpf(1.0f + __builtin_amdgcn_exp2f(-g * LOG2E));
;                         hv[i] = sg * up;
;                     }
;                     o[2 * n] = cvtpk(hv[0], hv[1]); o[2 * n + 1] = cvtpk(hv[2], hv[3]);
;                 }
;                 *(u32x4*)(H + (size_t)row * FF + col0) = (u32x4){o[0], o[1], o[2], o[3]};
.Lgu_epi_nobar:
	v_lshl_or_b32 v214, s76, 7, v155
	v_ashrrev_i32_e32 v215, 31, v214
	s_andn2_b64 vcc, exec, s[40:41]
	s_mov_b64 s[40:41], -1
	s_mul_i32 s92, s3, 24
	s_waitcnt vmcnt(0)
	v_add_f32_e32 v143, v170, v171
	v_add_f32_e32 v145, v172, v173
	v_add_f32_e32 v143, v143, v145
	v_add_f32_e32 v145, v174, v175
	v_add_f32_e32 v146, v176, v177
	v_add_f32_e32 v145, v145, v146
	v_add_f32_e32 v149, v178, v179
	v_add_f32_e32 v150, v180, v181
	v_add_f32_e32 v153, v182, v183
	v_add_f32_e32 v154, v184, v185
	v_add_f32_e32 v146, v149, v150
	v_add_f32_e32 v157, v198, v199
	v_add_f32_e32 v158, v200, v201
	v_add_f32_e32 v150, v157, v158
	v_mov_b32_e32 v158, v143
	v_add_f32_e32 v149, v153, v154
	s_nop 0
	v_permlane16_swap_b32_e32 v143, v158
	v_add_f32_e32 v163, v206, v207
	v_add_f32_e32 v165, v208, v209
	v_add_f32_e32 v154, v163, v165
	v_mov_b32_e32 v163, v149
	v_add_f32_e32 v143, v143, v158
	s_nop 0
	v_permlane16_swap_b32_e32 v149, v163
	v_mov_b32_e32 v158, v143
	v_add_f32_e32 v149, v149, v163
	s_nop 0
	v_permlane32_swap_b32_e32 v143, v158
	v_add_f32_e32 v143, v143, v158
	v_mov_b32_e32 v158, v149
	s_nop 1
	v_permlane32_swap_b32_e32 v149, v158
	v_add_f32_e32 v149, v149, v158
	v_mov_b32_e32 v158, v150
	s_nop 1
	v_permlane16_swap_b32_e32 v150, v158
	v_add_f32_e32 v150, v150, v158
	v_add_f32_e32 v161, v202, v203
	v_add_f32_e32 v162, v204, v205
	v_mov_b32_e32 v158, v150
	v_add_f32_e32 v153, v161, v162
	s_nop 0
	v_permlane32_swap_b32_e32 v150, v158
	v_add_f32_e32 v150, v150, v158
	v_mov_b32_e32 v158, v153
	s_nop 1
	v_permlane16_swap_b32_e32 v153, v158
	v_add_f32_e32 v153, v153, v158
	v_mov_b32_e32 v158, v153
	v_mov_b32_e32 v161, v145
	s_nop 0
	v_permlane32_swap_b32_e32 v153, v158
	v_mov_b32_e32 v162, v146
	v_permlane16_swap_b32_e32 v145, v161
	v_add_f32_e32 v153, v153, v158
	v_mov_b32_e32 v158, v154
	v_permlane16_swap_b32_e32 v146, v162
	v_add_f32_e32 v145, v145, v161
	v_permlane16_swap_b32_e32 v154, v158
	v_add_f32_e32 v146, v146, v162
	v_mov_b32_e32 v161, v145
	v_add_f32_e32 v154, v154, v158
	v_add_f32_e32 v166, v210, v211
	v_add_f32_e32 v167, v212, v213
	v_mov_b32_e32 v162, v146
	v_permlane32_swap_b32_e32 v145, v161
	v_mov_b32_e32 v158, v154
	v_add_f32_e32 v157, v166, v167
	v_permlane32_swap_b32_e32 v146, v162
	v_add_f32_e32 v145, v145, v161
	v_permlane32_swap_b32_e32 v154, v158
	v_fmamk_f32 v143, v143, 0x3a800000, v229
	v_add_f32_e32 v146, v146, v162
	v_add_f32_e32 v161, v154, v158
	v_mov_b32_e32 v154, v157
	v_rsq_f32_e32 v170, v143
	v_fmamk_f32 v143, v145, 0x3a800000, v229
	v_permlane16_swap_b32_e32 v157, v154
	v_rsq_f32_e32 v172, v143
	v_fmamk_f32 v143, v146, 0x3a800000, v229
	v_add_f32_e32 v154, v157, v154
	v_rsq_f32_e32 v166, v143
	v_fmamk_f32 v143, v149, 0x3a800000, v229
	v_mov_b32_e32 v157, v154
	v_rsq_f32_e32 v162, v143
	v_fmamk_f32 v143, v150, 0x3a800000, v229
	v_permlane32_swap_b32_e32 v154, v157
	v_rsq_f32_e32 v158, v143
	v_fmamk_f32 v143, v153, 0x3a800000, v229
	v_add_f32_e32 v157, v154, v157
	v_rsq_f32_e32 v154, v143
	v_fmamk_f32 v143, v161, 0x3a800000, v229
	v_rsq_f32_e32 v150, v143
	v_fmamk_f32 v143, v157, 0x3a800000, v229
	v_pk_mul_f32 v[126:127], v[126:127], v[170:171] op_sel_hi:[1,0]
	v_rsq_f32_e32 v146, v143
	v_mul_f32_e32 v143, 0xbfb8aa3b, v126
	v_exp_f32_e32 v143, v143
	v_mul_f32_e32 v145, 0xbfb8aa3b, v127
	v_exp_f32_e32 v145, v145
	v_pk_mul_f32 v[128:129], v[128:129], v[170:171] op_sel_hi:[1,0]
	v_add_f32_e32 v143, 1.0, v143
	v_rcp_f32_e32 v174, v143
	v_add_f32_e32 v143, 1.0, v145
	v_mul_f32_e32 v145, 0xbfb8aa3b, v128
	v_exp_f32_e32 v145, v145
	v_mul_f32_e32 v149, 0xbfb8aa3b, v129
	v_exp_f32_e32 v149, v149
	v_rcp_f32_e32 v175, v143
	v_add_f32_e32 v143, 1.0, v145
	v_rcp_f32_e32 v176, v143
	v_add_f32_e32 v143, 1.0, v149
	v_rcp_f32_e32 v177, v143
	v_pk_mul_f32 v[118:119], v[118:119], v[170:171] op_sel_hi:[1,0]
	v_pk_mul_f32 v[126:127], v[126:127], v[174:175]
	v_pk_mul_f32 v[122:123], v[122:123], v[170:171] op_sel_hi:[1,0]
	v_pk_mul_f32 v[118:119], v[118:119], v[126:127]
	v_pk_mul_f32 v[120:121], v[120:121], v[170:171] op_sel_hi:[1,0]
	v_pk_mul_f32 v[126:127], v[128:129], v[176:177]
	v_cvt_pk_bf16_f32 v118, v118, v119
	v_mul_f32_e32 v119, 0xbfb8aa3b, v122
	v_pk_mul_f32 v[120:121], v[120:121], v[126:127]
	v_exp_f32_e32 v126, v119
	v_cvt_pk_bf16_f32 v119, v120, v121
	v_mul_f32_e32 v120, 0xbfb8aa3b, v123
	v_pk_mul_f32 v[124:125], v[124:125], v[170:171] op_sel_hi:[1,0]
	v_exp_f32_e32 v121, v120
	v_add_f32_e32 v120, 1.0, v126
	v_mul_f32_e32 v126, 0xbfb8aa3b, v124
	v_mul_f32_e32 v127, 0xbfb8aa3b, v125
	v_exp_f32_e32 v126, v126
	v_exp_f32_e32 v127, v127
	v_add_f32_e32 v121, 1.0, v121
	v_rcp_f32_e32 v120, v120
	v_rcp_f32_e32 v121, v121
	v_add_f32_e32 v126, 1.0, v126
	v_add_f32_e32 v127, 1.0, v127
	v_rcp_f32_e32 v126, v126
	v_rcp_f32_e32 v127, v127
	v_pk_mul_f32 v[114:115], v[114:115], v[170:171] op_sel_hi:[1,0]
	v_pk_mul_f32 v[120:121], v[122:123], v[120:121]
	v_pk_mul_f32 v[116:117], v[116:117], v[170:171] op_sel_hi:[1,0]
	v_pk_mul_f32 v[114:115], v[114:115], v[120:121]
	v_pk_mul_f32 v[120:121], v[124:125], v[126:127]
	v_pk_mul_f32 v[110:111], v[110:111], v[172:173] op_sel_hi:[1,0]
	v_pk_mul_f32 v[116:117], v[116:117], v[120:121]
	v_cvt_pk_bf16_f32 v120, v114, v115
	v_mov_b64_e32 v[114:115], s[80:81]
	v_cvt_pk_bf16_f32 v121, v116, v117
	v_mad_i64_i32 v[122:123], s[76:77], v168, s8, v[114:115]
	v_lshlrev_b64 v[116:117], 1, v[214:215]
	v_lshl_add_u64 v[122:123], v[122:123], 0, v[116:117]
	v_mul_f32_e32 v124, 0xbfb8aa3b, v110
	global_store_dwordx4 v[122:123], v[118:121], off
	v_exp_f32_e32 v124, v124
	v_pk_mul_f32 v[112:113], v[112:113], v[172:173] op_sel_hi:[1,0]
	v_mul_f32_e32 v118, 0xbfb8aa3b, v111
	v_exp_f32_e32 v119, v118
; __device__ __forceinline__ unsigned cvtpk(float lo, float hi) { f32x2_t v = {lo, hi}; bf16x2_t b = __builtin_convertvector(v, bf16x2_t); return __builtin_bit_cast(unsigned, b); }
;     __device__ __forceinline__ void operator()(const f32x4 (&acc)[2][2][4][2], const pg8::Unit& u, int wr, int wc, int fr, int fq) const {
;     ...
;             for (int m = 0; m < 4; ++m) {
;                 const int row = row0 + ai * 128 + m * 16;
;                 const float r = rr[ai * 4 + m];
;                 unsigned o[4];
; #pragma unroll
;                 for (int n = 0; n < 2; ++n) {
;                     float hv[4];
; #pragma unroll
;                     for (int i = 0; i < 4; ++i) {
;                         const float g = acc[ai][0][m][n][i] * r, up = acc[ai][1][m][n][i] * r;
;                         const float sg = g * __builtin_amdgcn_rcpf(1.0f + __builtin_amdgcn_exp2f(-g * LOG2E));
;                         hv[i] = sg * up;
;                     }
;                     o[2 * n] = cvtpk(hv[0], hv[1]); o[2 * n + 1] = cvtpk(hv[2], hv[3]);
;                 }
;                 *(u32x4*)(H + (size_t)row * FF + col0) = (u32x4){o[0], o[1], o[2], o[3]};
	v_mul_f32_e32 v120, 0xbfb8aa3b, v112
	v_mul_f32_e32 v121, 0xbfb8aa3b, v113
	v_exp_f32_e32 v120, v120
	v_exp_f32_e32 v121, v121
	v_add_f32_e32 v118, 1.0, v124
	v_add_f32_e32 v119, 1.0, v119
	v_rcp_f32_e32 v118, v118
	v_rcp_f32_e32 v119, v119
	v_add_f32_e32 v120, 1.0, v120
	v_add_f32_e32 v121, 1.0, v121
	v_rcp_f32_e32 v120, v120
	v_rcp_f32_e32 v121, v121
	v_pk_mul_f32 v[102:103], v[102:103], v[172:173] op_sel_hi:[1,0]
	v_pk_mul_f32 v[110:111], v[110:111], v[118:119]
	v_pk_mul_f32 v[106:107], v[106:107], v[172:173] op_sel_hi:[1,0]
	v_pk_mul_f32 v[102:103], v[102:103], v[110:111]
	v_pk_mul_f32 v[104:105], v[104:105], v[172:173] op_sel_hi:[1,0]
	v_pk_mul_f32 v[110:111], v[112:113], v[120:121]
	v_cvt_pk_bf16_f32 v102, v102, v103
	v_mul_f32_e32 v103, 0xbfb8aa3b, v106
	v_pk_mul_f32 v[104:105], v[104:105], v[110:111]
	v_exp_f32_e32 v110, v103
	v_cvt_pk_bf16_f32 v103, v104, v105
	v_mul_f32_e32 v104, 0xbfb8aa3b, v107
	v_pk_mul_f32 v[108:109], v[108:109], v[172:173] op_sel_hi:[1,0]
	v_exp_f32_e32 v105, v104
	v_add_f32_e32 v104, 1.0, v110
	v_mul_f32_e32 v110, 0xbfb8aa3b, v108
	v_mul_f32_e32 v111, 0xbfb8aa3b, v109
	v_exp_f32_e32 v110, v110
	v_exp_f32_e32 v111, v111
	v_add_f32_e32 v105, 1.0, v105
	v_rcp_f32_e32 v104, v104
	v_rcp_f32_e32 v105, v105
	v_add_f32_e32 v110, 1.0, v110
	v_add_f32_e32 v111, 1.0, v111
	v_rcp_f32_e32 v110, v110
	v_rcp_f32_e32 v111, v111
	v_pk_mul_f32 v[98:99], v[98:99], v[172:173] op_sel_hi:[1,0]
	v_pk_mul_f32 v[104:105], v[106:107], v[104:105]
	v_pk_mul_f32 v[100:101], v[100:101], v[172:173] op_sel_hi:[1,0]
	v_pk_mul_f32 v[98:99], v[98:99], v[104:105]
	v_pk_mul_f32 v[104:105], v[108:109], v[110:111]
	v_pk_mul_f32 v[94:95], v[94:95], v[166:167] op_sel_hi:[1,0]
	v_pk_mul_f32 v[100:101], v[100:101], v[104:105]
	v_cvt_pk_bf16_f32 v104, v98, v99
	v_cvt_pk_bf16_f32 v105, v100, v101
	v_mul_f32_e32 v100, 0xbfb8aa3b, v94
	v_mad_i64_i32 v[98:99], s[76:77], v164, s8, v[114:115]
	v_exp_f32_e32 v100, v100
	v_lshl_add_u64 v[98:99], v[98:99], 0, v[116:117]
	global_store_dwordx4 v[98:99], v[102:105], off
	v_mul_f32_e32 v98, 0xbfb8aa3b, v95
	v_exp_f32_e32 v99, v98
	v_pk_mul_f32 v[96:97], v[96:97], v[166:167] op_sel_hi:[1,0]
	v_add_f32_e32 v98, 1.0, v100
	v_mul_f32_e32 v100, 0xbfb8aa3b, v96
	v_mul_f32_e32 v101, 0xbfb8aa3b, v97
	v_exp_f32_e32 v100, v100
	v_exp_f32_e32 v101, v101
	v_add_f32_e32 v99, 1.0, v99
	v_rcp_f32_e32 v98, v98
	v_rcp_f32_e32 v99, v99
	v_add_f32_e32 v100, 1.0, v100
	v_add_f32_e32 v101, 1.0, v101
	v_rcp_f32_e32 v100, v100
	v_rcp_f32_e32 v101, v101
	v_pk_mul_f32 v[86:87], v[86:87], v[166:167] op_sel_hi:[1,0]
	v_pk_mul_f32 v[94:95], v[94:95], v[98:99]
	v_pk_mul_f32 v[90:91], v[90:91], v[166:167] op_sel_hi:[1,0]
	v_pk_mul_f32 v[86:87], v[86:87], v[94:95]
	v_pk_mul_f32 v[88:89], v[88:89], v[166:167] op_sel_hi:[1,0]
	v_pk_mul_f32 v[94:95], v[96:97], v[100:101]
	v_cvt_pk_bf16_f32 v86, v86, v87
	v_mul_f32_e32 v87, 0xbfb8aa3b, v90
	v_pk_mul_f32 v[88:89], v[88:89], v[94:95]
	v_exp_f32_e32 v94, v87
	v_cvt_pk_bf16_f32 v87, v88, v89
	v_mul_f32_e32 v88, 0xbfb8aa3b, v91
	v_pk_mul_f32 v[92:93], v[92:93], v[166:167] op_sel_hi:[1,0]
	v_exp_f32_e32 v89, v88
	v_add_f32_e32 v88, 1.0, v94
	v_mul_f32_e32 v94, 0xbfb8aa3b, v92
	v_mul_f32_e32 v95, 0xbfb8aa3b, v93
	v_exp_f32_e32 v94, v94
	v_exp_f32_e32 v95, v95
	v_add_f32_e32 v89, 1.0, v89
	v_rcp_f32_e32 v88, v88
	v_rcp_f32_e32 v89, v89
	v_add_f32_e32 v94, 1.0, v94
	v_add_f32_e32 v95, 1.0, v95
	v_rcp_f32_e32 v94, v94
	v_rcp_f32_e32 v95, v95
	v_pk_mul_f32 v[82:83], v[82:83], v[166:167] op_sel_hi:[1,0]
	v_pk_mul_f32 v[88:89], v[90:91], v[88:89]
	v_pk_mul_f32 v[84:85], v[84:85], v[166:167] op_sel_hi:[1,0]
	v_pk_mul_f32 v[82:83], v[82:83], v[88:89]
	v_pk_mul_f32 v[88:89], v[92:93], v[94:95]
	v_pk_mul_f32 v[78:79], v[78:79], v[162:163] op_sel_hi:[1,0]
	v_pk_mul_f32 v[84:85], v[84:85], v[88:89]
	v_cvt_pk_bf16_f32 v88, v82, v83
	v_cvt_pk_bf16_f32 v89, v84, v85
	v_mul_f32_e32 v84, 0xbfb8aa3b, v78
	v_mad_i64_i32 v[82:83], s[76:77], v160, s8, v[114:115]
	v_exp_f32_e32 v84, v84
	v_lshl_add_u64 v[82:83], v[82:83], 0, v[116:117]
	global_store_dwordx4 v[82:83], v[86:89], off
	v_mul_f32_e32 v82, 0xbfb8aa3b, v79
	v_exp_f32_e32 v83, v82
	v_pk_mul_f32 v[80:81], v[80:81], v[162:163] op_sel_hi:[1,0]
	v_add_f32_e32 v82, 1.0, v84
	v_mul_f32_e32 v84, 0xbfb8aa3b, v80
	v_mul_f32_e32 v85, 0xbfb8aa3b, v81
	v_exp_f32_e32 v84, v84
	v_exp_f32_e32 v85, v85
	v_add_f32_e32 v83, 1.0, v83
	v_rcp_f32_e32 v82, v82
	v_rcp_f32_e32 v83, v83
	v_add_f32_e32 v84, 1.0, v84
	v_add_f32_e32 v85, 1.0, v85
	v_rcp_f32_e32 v84, v84
	v_rcp_f32_e32 v85, v85
	v_pk_mul_f32 v[70:71], v[70:71], v[162:163] op_sel_hi:[1,0]
	v_pk_mul_f32 v[78:79], v[78:79], v[82:83]
	v_pk_mul_f32 v[74:75], v[74:75], v[162:163] op_sel_hi:[1,0]
	v_pk_mul_f32 v[70:71], v[70:71], v[78:79]
	v_pk_mul_f32 v[72:73], v[72:73], v[162:163] op_sel_hi:[1,0]
	v_pk_mul_f32 v[78:79], v[80:81], v[84:85]
	v_cvt_pk_bf16_f32 v70, v70, v71
	v_mul_f32_e32 v71, 0xbfb8aa3b, v74
	v_pk_mul_f32 v[72:73], v[72:73], v[78:79]
	v_exp_f32_e32 v78, v71
	v_cvt_pk_bf16_f32 v71, v72, v73
	v_mul_f32_e32 v72, 0xbfb8aa3b, v75
	v_pk_mul_f32 v[76:77], v[76:77], v[162:163] op_sel_hi:[1,0]
	v_exp_f32_e32 v73, v72
	v_add_f32_e32 v72, 1.0, v78
	v_mul_f32_e32 v78, 0xbfb8aa3b, v76
	v_mul_f32_e32 v79, 0xbfb8aa3b, v77
	v_exp_f32_e32 v78, v78
	v_exp_f32_e32 v79, v79
	v_add_f32_e32 v73, 1.0, v73
	v_rcp_f32_e32 v72, v72
	v_rcp_f32_e32 v73, v73
	v_add_f32_e32 v78, 1.0, v78
	v_add_f32_e32 v79, 1.0, v79
	v_rcp_f32_e32 v78, v78
	v_rcp_f32_e32 v79, v79
	v_pk_mul_f32 v[66:67], v[66:67], v[162:163] op_sel_hi:[1,0]
	v_pk_mul_f32 v[72:73], v[74:75], v[72:73]
	v_pk_mul_f32 v[68:69], v[68:69], v[162:163] op_sel_hi:[1,0]
; __device__ __forceinline__ unsigned cvtpk(float lo, float hi) { f32x2_t v = {lo, hi}; bf16x2_t b = __builtin_convertvector(v, bf16x2_t); return __builtin_bit_cast(unsigned, b); }
;     __device__ __forceinline__ void operator()(const f32x4 (&acc)[2][2][4][2], const pg8::Unit& u, int wr, int wc, int fr, int fq) const {
;     ...
;             for (int m = 0; m < 4; ++m) {
;                 const int row = row0 + ai * 128 + m * 16;
;                 const float r = rr[ai * 4 + m];
;                 unsigned o[4];
; #pragma unroll
;                 for (int n = 0; n < 2; ++n) {
;                     float hv[4];
; #pragma unroll
;                     for (int i = 0; i < 4; ++i) {
;                         const float g = acc[ai][0][m][n][i] * r, up = acc[ai][1][m][n][i] * r;
;                         const float sg = g * __builtin_amdgcn_rcpf(1.0f + __builtin_amdgcn_exp2f(-g * LOG2E));
;                         hv[i] = sg * up;
;                     }
;                     o[2 * n] = cvtpk(hv[0], hv[1]); o[2 * n + 1] = cvtpk(hv[2], hv[3]);
;                 }
;                 *(u32x4*)(H + (size_t)row * FF + col0) = (u32x4){o[0], o[1], o[2], o[3]};
	v_pk_mul_f32 v[66:67], v[66:67], v[72:73]
	v_pk_mul_f32 v[72:73], v[76:77], v[78:79]
	v_pk_mul_f32 v[62:63], v[62:63], v[158:159] op_sel_hi:[1,0]
	v_pk_mul_f32 v[68:69], v[68:69], v[72:73]
	v_cvt_pk_bf16_f32 v72, v66, v67
	v_cvt_pk_bf16_f32 v73, v68, v69
	v_mul_f32_e32 v68, 0xbfb8aa3b, v62
	v_mad_i64_i32 v[66:67], s[76:77], v156, s8, v[114:115]
	v_exp_f32_e32 v68, v68
	v_lshl_add_u64 v[66:67], v[66:67], 0, v[116:117]
	global_store_dwordx4 v[66:67], v[70:73], off
	v_mul_f32_e32 v66, 0xbfb8aa3b, v63
	v_exp_f32_e32 v67, v66
	v_pk_mul_f32 v[64:65], v[64:65], v[158:159] op_sel_hi:[1,0]
	v_add_f32_e32 v66, 1.0, v68
	v_mul_f32_e32 v68, 0xbfb8aa3b, v64
	v_mul_f32_e32 v69, 0xbfb8aa3b, v65
	v_exp_f32_e32 v68, v68
	v_exp_f32_e32 v69, v69
	v_add_f32_e32 v67, 1.0, v67
	v_rcp_f32_e32 v66, v66
	v_rcp_f32_e32 v67, v67
	v_add_f32_e32 v68, 1.0, v68
	v_add_f32_e32 v69, 1.0, v69
	v_rcp_f32_e32 v68, v68
	v_rcp_f32_e32 v69, v69
	v_pk_mul_f32 v[54:55], v[54:55], v[158:159] op_sel_hi:[1,0]
	v_pk_mul_f32 v[62:63], v[62:63], v[66:67]
	v_pk_mul_f32 v[58:59], v[58:59], v[158:159] op_sel_hi:[1,0]
	v_pk_mul_f32 v[54:55], v[54:55], v[62:63]
	v_pk_mul_f32 v[56:57], v[56:57], v[158:159] op_sel_hi:[1,0]
	v_pk_mul_f32 v[62:63], v[64:65], v[68:69]
	v_cvt_pk_bf16_f32 v54, v54, v55
	v_mul_f32_e32 v55, 0xbfb8aa3b, v58
	v_pk_mul_f32 v[56:57], v[56:57], v[62:63]
	v_exp_f32_e32 v62, v55
	v_cvt_pk_bf16_f32 v55, v56, v57
	v_mul_f32_e32 v56, 0xbfb8aa3b, v59
	v_pk_mul_f32 v[60:61], v[60:61], v[158:159] op_sel_hi:[1,0]
	v_exp_f32_e32 v57, v56
	v_add_f32_e32 v56, 1.0, v62
	v_mul_f32_e32 v62, 0xbfb8aa3b, v60
	v_mul_f32_e32 v63, 0xbfb8aa3b, v61
	v_exp_f32_e32 v62, v62
	v_exp_f32_e32 v63, v63
	v_add_f32_e32 v57, 1.0, v57
	v_rcp_f32_e32 v56, v56
	v_rcp_f32_e32 v57, v57
	v_add_f32_e32 v62, 1.0, v62
	v_add_f32_e32 v63, 1.0, v63
	v_rcp_f32_e32 v62, v62
	v_rcp_f32_e32 v63, v63
	v_pk_mul_f32 v[50:51], v[50:51], v[158:159] op_sel_hi:[1,0]
	v_pk_mul_f32 v[56:57], v[58:59], v[56:57]
	v_pk_mul_f32 v[52:53], v[52:53], v[158:159] op_sel_hi:[1,0]
	v_pk_mul_f32 v[50:51], v[50:51], v[56:57]
	v_pk_mul_f32 v[56:57], v[60:61], v[62:63]
	v_pk_mul_f32 v[46:47], v[46:47], v[154:155] op_sel_hi:[1,0]
	v_pk_mul_f32 v[52:53], v[52:53], v[56:57]
	v_cvt_pk_bf16_f32 v56, v50, v51
	v_cvt_pk_bf16_f32 v57, v52, v53
	v_mul_f32_e32 v52, 0xbfb8aa3b, v46
	v_mad_i64_i32 v[50:51], s[76:77], v152, s8, v[114:115]
	v_exp_f32_e32 v52, v52
	v_lshl_add_u64 v[50:51], v[50:51], 0, v[116:117]
	global_store_dwordx4 v[50:51], v[54:57], off
	v_mul_f32_e32 v50, 0xbfb8aa3b, v47
	v_exp_f32_e32 v51, v50
	v_pk_mul_f32 v[48:49], v[48:49], v[154:155] op_sel_hi:[1,0]
	v_add_f32_e32 v50, 1.0, v52
	v_mul_f32_e32 v52, 0xbfb8aa3b, v48
	v_mul_f32_e32 v53, 0xbfb8aa3b, v49
	v_exp_f32_e32 v52, v52
	v_exp_f32_e32 v53, v53
	v_add_f32_e32 v51, 1.0, v51
	v_rcp_f32_e32 v50, v50
	v_rcp_f32_e32 v51, v51
	v_add_f32_e32 v52, 1.0, v52
	v_add_f32_e32 v53, 1.0, v53
	v_rcp_f32_e32 v52, v52
	v_rcp_f32_e32 v53, v53
	v_pk_mul_f32 v[38:39], v[38:39], v[154:155] op_sel_hi:[1,0]
	v_pk_mul_f32 v[46:47], v[46:47], v[50:51]
	v_pk_mul_f32 v[42:43], v[42:43], v[154:155] op_sel_hi:[1,0]
	v_pk_mul_f32 v[38:39], v[38:39], v[46:47]
	v_pk_mul_f32 v[40:41], v[40:41], v[154:155] op_sel_hi:[1,0]
	v_pk_mul_f32 v[46:47], v[48:49], v[52:53]
	v_cvt_pk_bf16_f32 v38, v38, v39
	v_mul_f32_e32 v39, 0xbfb8aa3b, v42
	v_pk_mul_f32 v[40:41], v[40:41], v[46:47]
	v_exp_f32_e32 v46, v39
	v_cvt_pk_bf16_f32 v39, v40, v41
	v_mul_f32_e32 v40, 0xbfb8aa3b, v43
	v_pk_mul_f32 v[44:45], v[44:45], v[154:155] op_sel_hi:[1,0]
	v_exp_f32_e32 v41, v40
	v_add_f32_e32 v40, 1.0, v46
	v_mul_f32_e32 v46, 0xbfb8aa3b, v44
	v_mul_f32_e32 v47, 0xbfb8aa3b, v45
	v_exp_f32_e32 v46, v46
	v_exp_f32_e32 v47, v47
	v_add_f32_e32 v41, 1.0, v41
	v_rcp_f32_e32 v40, v40
	v_rcp_f32_e32 v41, v41
	v_add_f32_e32 v46, 1.0, v46
	v_add_f32_e32 v47, 1.0, v47
	v_rcp_f32_e32 v46, v46
	v_rcp_f32_e32 v47, v47
	v_pk_mul_f32 v[34:35], v[34:35], v[154:155] op_sel_hi:[1,0]
	v_pk_mul_f32 v[40:41], v[42:43], v[40:41]
	v_pk_mul_f32 v[36:37], v[36:37], v[154:155] op_sel_hi:[1,0]
	v_pk_mul_f32 v[34:35], v[34:35], v[40:41]
	v_pk_mul_f32 v[40:41], v[44:45], v[46:47]
	v_pk_mul_f32 v[30:31], v[30:31], v[150:151] op_sel_hi:[1,0]
	v_pk_mul_f32 v[36:37], v[36:37], v[40:41]
; #define PG8_BAR __builtin_amdgcn_s_barrier()
; __device__ __forceinline__ unsigned cvtpk(float lo, float hi) { f32x2_t v = {lo, hi}; bf16x2_t b = __builtin_convertvector(v, bf16x2_t); return __builtin_bit_cast(unsigned, b); }
; template <class Epi, class Sched, bool ALIGN_EPI = false, bool SP2 = false>
; __device__ __forceinline__ void gemm_phase(PG8_LAS unsigned char* lds, const Gemm g, const Sched& S, const Epi& E) {
;     ...
;         if (!has_next) break;
; #pragma unroll
;         for (int a = 0; a < 2; ++a)
; #pragma unroll
;             for (int b = 0; b < 2; ++b)
; #pragma unroll
;                 for (int m = 0; m < 4; ++m)
; #pragma unroll
;                     for (int n = 0; n < 2; ++n) acc[a][b][m][n] = (f32x4){0.f, 0.f, 0.f, 0.f};
;         cur = nxt; cA = nA; cB = nB; ++ui;
;         if constexpr (ALIGN_EPI) { if (wr == 1) PG8_BAR; }
;     __device__ __forceinline__ void operator()(const f32x4 (&acc)[2][2][4][2], const pg8::Unit& u, int wr, int wc, int fr, int fq) const {
;     ...
;             for (int m = 0; m < 4; ++m) {
;                 const int row = row0 + ai * 128 + m * 16;
;                 const float r = rr[ai * 4 + m];
;                 unsigned o[4];
; #pragma unroll
;                 for (int n = 0; n < 2; ++n) {
;                     float hv[4];
; #pragma unroll
;                     for (int i = 0; i < 4; ++i) {
;                         const float g = acc[ai][0][m][n][i] * r, up = acc[ai][1][m][n][i] * r;
;                         const float sg = g * __builtin_amdgcn_rcpf(1.0f + __builtin_amdgcn_exp2f(-g * LOG2E));
;                         hv[i] = sg * up;
;                     }
;                     o[2 * n] = cvtpk(hv[0], hv[1]); o[2 * n + 1] = cvtpk(hv[2], hv[3]);
;                 }
;                 *(u32x4*)(H + (size_t)row * FF + col0) = (u32x4){o[0], o[1], o[2], o[3]};
	v_cvt_pk_bf16_f32 v40, v34, v35
	v_cvt_pk_bf16_f32 v41, v36, v37
	v_mul_f32_e32 v36, 0xbfb8aa3b, v30
	v_mad_i64_i32 v[34:35], s[76:77], v148, s8, v[114:115]
	v_exp_f32_e32 v36, v36
	v_lshl_add_u64 v[34:35], v[34:35], 0, v[116:117]
	global_store_dwordx4 v[34:35], v[38:41], off
	v_mul_f32_e32 v34, 0xbfb8aa3b, v31
	v_exp_f32_e32 v35, v34
	v_pk_mul_f32 v[32:33], v[32:33], v[150:151] op_sel_hi:[1,0]
	v_add_f32_e32 v34, 1.0, v36
	v_mul_f32_e32 v36, 0xbfb8aa3b, v32
	v_mul_f32_e32 v37, 0xbfb8aa3b, v33
	v_exp_f32_e32 v36, v36
	v_exp_f32_e32 v37, v37
	v_add_f32_e32 v35, 1.0, v35
	v_rcp_f32_e32 v34, v34
	v_rcp_f32_e32 v35, v35
	v_add_f32_e32 v36, 1.0, v36
	v_add_f32_e32 v37, 1.0, v37
	v_rcp_f32_e32 v36, v36
	v_rcp_f32_e32 v37, v37
	v_pk_mul_f32 v[22:23], v[22:23], v[150:151] op_sel_hi:[1,0]
	v_pk_mul_f32 v[30:31], v[30:31], v[34:35]
	v_pk_mul_f32 v[26:27], v[26:27], v[150:151] op_sel_hi:[1,0]
	v_pk_mul_f32 v[22:23], v[22:23], v[30:31]
	v_pk_mul_f32 v[24:25], v[24:25], v[150:151] op_sel_hi:[1,0]
	v_pk_mul_f32 v[30:31], v[32:33], v[36:37]
	v_cvt_pk_bf16_f32 v22, v22, v23
	v_mul_f32_e32 v23, 0xbfb8aa3b, v26
	v_pk_mul_f32 v[24:25], v[24:25], v[30:31]
	v_exp_f32_e32 v30, v23
	v_cvt_pk_bf16_f32 v23, v24, v25
	v_mul_f32_e32 v24, 0xbfb8aa3b, v27
	v_pk_mul_f32 v[28:29], v[28:29], v[150:151] op_sel_hi:[1,0]
	v_exp_f32_e32 v25, v24
	v_add_f32_e32 v24, 1.0, v30
	v_mul_f32_e32 v30, 0xbfb8aa3b, v28
	v_mul_f32_e32 v31, 0xbfb8aa3b, v29
	v_exp_f32_e32 v30, v30
	v_exp_f32_e32 v31, v31
	v_add_f32_e32 v25, 1.0, v25
	v_rcp_f32_e32 v24, v24
	v_rcp_f32_e32 v25, v25
	v_add_f32_e32 v30, 1.0, v30
	v_add_f32_e32 v31, 1.0, v31
	v_rcp_f32_e32 v30, v30
	v_rcp_f32_e32 v31, v31
	v_pk_mul_f32 v[18:19], v[18:19], v[150:151] op_sel_hi:[1,0]
	v_pk_mul_f32 v[24:25], v[26:27], v[24:25]
	v_pk_mul_f32 v[20:21], v[20:21], v[150:151] op_sel_hi:[1,0]
	v_pk_mul_f32 v[18:19], v[18:19], v[24:25]
	v_pk_mul_f32 v[24:25], v[28:29], v[30:31]
	v_pk_mul_f32 v[14:15], v[14:15], v[146:147] op_sel_hi:[1,0]
	v_pk_mul_f32 v[20:21], v[20:21], v[24:25]
	v_cvt_pk_bf16_f32 v24, v18, v19
	v_cvt_pk_bf16_f32 v25, v20, v21
	v_mul_f32_e32 v20, 0xbfb8aa3b, v14
	v_mad_i64_i32 v[18:19], s[76:77], v144, s8, v[114:115]
	v_exp_f32_e32 v20, v20
	v_lshl_add_u64 v[18:19], v[18:19], 0, v[116:117]
	global_store_dwordx4 v[18:19], v[22:25], off
	v_mul_f32_e32 v18, 0xbfb8aa3b, v15
	v_exp_f32_e32 v19, v18
	v_pk_mul_f32 v[16:17], v[16:17], v[146:147] op_sel_hi:[1,0]
	v_add_f32_e32 v18, 1.0, v20
	v_mul_f32_e32 v20, 0xbfb8aa3b, v16
	v_mul_f32_e32 v21, 0xbfb8aa3b, v17
	v_exp_f32_e32 v20, v20
	v_exp_f32_e32 v21, v21
	v_add_f32_e32 v19, 1.0, v19
	v_rcp_f32_e32 v18, v18
	v_rcp_f32_e32 v19, v19
	v_add_f32_e32 v20, 1.0, v20
	v_add_f32_e32 v21, 1.0, v21
	v_rcp_f32_e32 v20, v20
	v_rcp_f32_e32 v21, v21
	v_pk_mul_f32 v[6:7], v[6:7], v[146:147] op_sel_hi:[1,0]
	v_pk_mul_f32 v[14:15], v[14:15], v[18:19]
	v_pk_mul_f32 v[10:11], v[10:11], v[146:147] op_sel_hi:[1,0]
	v_pk_mul_f32 v[6:7], v[6:7], v[14:15]
	v_pk_mul_f32 v[8:9], v[8:9], v[146:147] op_sel_hi:[1,0]
	v_pk_mul_f32 v[14:15], v[16:17], v[20:21]
	v_cvt_pk_bf16_f32 v6, v6, v7
	v_mul_f32_e32 v7, 0xbfb8aa3b, v10
	v_pk_mul_f32 v[8:9], v[8:9], v[14:15]
	v_exp_f32_e32 v14, v7
	v_cvt_pk_bf16_f32 v7, v8, v9
	v_mul_f32_e32 v8, 0xbfb8aa3b, v11
	v_pk_mul_f32 v[12:13], v[12:13], v[146:147] op_sel_hi:[1,0]
	v_exp_f32_e32 v9, v8
	v_add_f32_e32 v8, 1.0, v14
	v_mul_f32_e32 v14, 0xbfb8aa3b, v12
	v_mul_f32_e32 v15, 0xbfb8aa3b, v13
	v_exp_f32_e32 v14, v14
	v_exp_f32_e32 v15, v15
	v_add_f32_e32 v9, 1.0, v9
	v_rcp_f32_e32 v8, v8
	v_rcp_f32_e32 v9, v9
	v_add_f32_e32 v14, 1.0, v14
	v_add_f32_e32 v15, 1.0, v15
	v_rcp_f32_e32 v14, v14
	v_rcp_f32_e32 v15, v15
	v_pk_mul_f32 v[2:3], v[2:3], v[146:147] op_sel_hi:[1,0]
	v_pk_mul_f32 v[8:9], v[10:11], v[8:9]
	v_pk_mul_f32 v[4:5], v[4:5], v[146:147] op_sel_hi:[1,0]
	v_pk_mul_f32 v[2:3], v[2:3], v[8:9]
	v_pk_mul_f32 v[8:9], v[12:13], v[14:15]
	s_nop 0
	v_pk_mul_f32 v[4:5], v[4:5], v[8:9]
	v_cvt_pk_bf16_f32 v8, v2, v3
	v_mad_i64_i32 v[2:3], s[76:77], v142, s8, v[114:115]
	v_cvt_pk_bf16_f32 v9, v4, v5
	v_lshl_add_u64 v[2:3], v[2:3], 0, v[116:117]
	global_store_dwordx4 v[2:3], v[6:9], off
	s_cbranch_vccnz .LBB0_271
	s_andn2_b64 vcc, exec, s[44:45]
	s_cbranch_vccnz .LBB0_270
	s_barrier
	s_branch .LBB0_270
